# v14 + first-two in-loop vmcnt waits relaxed after an epilogue (6 GEMM instances) + s_setprio removed from K-loops
# baseline (speedup 1.0000x reference)
_Z10fwd_kernel4Args:
	s_mov_b32 s101, 0
	s_load_dword s85, s[0:1], 0x1b8
	s_mov_b64 s[48:49], s[0:1]
	s_add_u32 s0, s48, 0x1b8
	s_addc_u32 s1, s49, 0
	s_mov_b32 s97, s2
	v_writelane_b32 v253, s0, 0
	v_readfirstlane_b32 s18, v0
	s_mov_b32 s89, s2
	v_writelane_b32 v253, s1, 1
	s_waitcnt lgkmcnt(0)
	s_and_b32 s0, s85, 7
	s_cmp_lg_u32 s0, 0
	s_cbranch_scc1 .LBB0_2
	s_ashr_i32 s1, s97, 31
	s_lshr_b32 s1, s1, 29
	s_add_i32 s1, s97, s1
	s_ashr_i32 s2, s1, 3
	s_and_b32 s1, s1, -8
	s_ashr_i32 s0, s85, 3
	s_sub_i32 s1, s97, s1
	s_mul_i32 s0, s0, s1
	s_add_i32 s89, s0, s2

.LBB0_293:
	s_add_i32 s43, s28, 2
	s_add_u32 s53, s40, 0x80
	s_addc_u32 s29, s41, 0
	s_add_i32 s72, 0, 0x10000
	s_cmp_eq_u32 s49, s28
	s_cselect_b32 s29, s61, s29
	s_cselect_b32 s28, s60, s53
	v_add_u32_e32 v128, s72, v181
	s_cselect_b32 s71, s65, s42
	s_cselect_b32 s70, s64, s33
	s_add_i32 s53, 0, 0x14000
	ds_read_b128 v[130:133], v128
	ds_read_b128 v[134:137], v128 offset:1024
	ds_read_b128 v[138:141], v128 offset:2048
	ds_read_b128 v[142:145], v128 offset:3072
	v_add_u32_e32 v128, s53, v181
	s_waitcnt lgkmcnt(0)
	ds_read_b128 v[162:165], v128
	ds_read_b128 v[166:169], v128 offset:1024
	ds_read_b128 v[170:173], v128 offset:2048
	ds_read_b128 v[174:177], v128 offset:3072
	v_lshl_add_u64 v[178:179], s[40:41], 0, v[158:159]
	s_add_i32 m0, s90, 0xc000
	ds_read_b128 v[186:189], v183
	ds_read_b128 v[190:193], v183 offset:1024
	ds_read_b128 v[194:197], v183 offset:2048
	ds_read_b128 v[198:201], v183 offset:3072
	ds_read_b128 v[202:205], v183 offset:4096
	ds_read_b128 v[206:209], v183 offset:5120
	ds_read_b128 v[210:213], v183 offset:6144
	ds_read_b128 v[214:217], v183 offset:7168
	global_load_lds_dwordx4 v[178:179], off
	v_lshl_add_u64 v[178:179], s[40:41], 0, v[160:161]
	s_add_i32 m0, s90, 0xe000
	s_nop 0
	global_load_lds_dwordx4 v[178:179], off
	s_waitcnt vmcnt(8)
	s_waitcnt lgkmcnt(0)
	s_barrier
	s_waitcnt lgkmcnt(0)
	v_mfma_f32_16x16x32_bf16 v[112:115], v[130:133], v[186:189], v[112:115]
	v_mfma_f32_16x16x32_bf16 v[120:123], v[138:141], v[186:189], v[120:123]
	v_mfma_f32_16x16x32_bf16 v[96:99], v[130:133], v[194:197], v[96:99]
	v_mfma_f32_16x16x32_bf16 v[104:107], v[138:141], v[194:197], v[104:107]
	v_mfma_f32_16x16x32_bf16 v[80:83], v[130:133], v[202:205], v[80:83]
	v_mfma_f32_16x16x32_bf16 v[88:91], v[138:141], v[202:205], v[88:91]
	v_mfma_f32_16x16x32_bf16 v[64:67], v[130:133], v[210:213], v[64:67]
	v_mfma_f32_16x16x32_bf16 v[72:75], v[138:141], v[210:213], v[72:75]
	v_mfma_f32_16x16x32_bf16 v[112:115], v[134:137], v[190:193], v[112:115]
	v_mfma_f32_16x16x32_bf16 v[120:123], v[142:145], v[190:193], v[120:123]
	v_mfma_f32_16x16x32_bf16 v[96:99], v[134:137], v[198:201], v[96:99]
	v_mfma_f32_16x16x32_bf16 v[104:107], v[142:145], v[198:201], v[104:107]
	v_mfma_f32_16x16x32_bf16 v[80:83], v[134:137], v[206:209], v[80:83]
	v_mfma_f32_16x16x32_bf16 v[88:91], v[142:145], v[206:209], v[88:91]
	v_mfma_f32_16x16x32_bf16 v[64:67], v[134:137], v[214:217], v[64:67]
	v_mfma_f32_16x16x32_bf16 v[72:75], v[142:145], v[214:217], v[72:75]
	v_mfma_f32_16x16x32_bf16 v[116:119], v[162:165], v[186:189], v[116:119]
	v_mfma_f32_16x16x32_bf16 v[124:127], v[170:173], v[186:189], v[124:127]
	v_mfma_f32_16x16x32_bf16 v[100:103], v[162:165], v[194:197], v[100:103]
	v_mfma_f32_16x16x32_bf16 v[108:111], v[170:173], v[194:197], v[108:111]
	v_mfma_f32_16x16x32_bf16 v[84:87], v[162:165], v[202:205], v[84:87]
	v_mfma_f32_16x16x32_bf16 v[92:95], v[170:173], v[202:205], v[92:95]
	v_mfma_f32_16x16x32_bf16 v[68:71], v[162:165], v[210:213], v[68:71]
	v_mfma_f32_16x16x32_bf16 v[76:79], v[170:173], v[210:213], v[76:79]
	v_mfma_f32_16x16x32_bf16 v[116:119], v[166:169], v[190:193], v[116:119]
	v_mfma_f32_16x16x32_bf16 v[124:127], v[174:177], v[190:193], v[124:127]
	v_mfma_f32_16x16x32_bf16 v[100:103], v[166:169], v[198:201], v[100:103]
	v_mfma_f32_16x16x32_bf16 v[108:111], v[174:177], v[198:201], v[108:111]
	v_mfma_f32_16x16x32_bf16 v[84:87], v[166:169], v[206:209], v[84:87]
	v_mfma_f32_16x16x32_bf16 v[92:95], v[174:177], v[206:209], v[92:95]
	v_mfma_f32_16x16x32_bf16 v[68:71], v[166:169], v[214:217], v[68:71]
	v_mfma_f32_16x16x32_bf16 v[76:79], v[174:177], v[214:217], v[76:79]
	s_barrier
	s_add_i32 s72, s72, s87
	v_lshl_add_u64 v[178:179], s[70:71], 0, v[150:151]
	s_mov_b32 m0, s72
	ds_read_b128 v[186:189], v183 offset:16384
	ds_read_b128 v[190:193], v183 offset:17408
	ds_read_b128 v[194:197], v183 offset:18432
	ds_read_b128 v[198:201], v183 offset:19456
	ds_read_b128 v[202:205], v183 offset:20480
	ds_read_b128 v[206:209], v183 offset:21504
	ds_read_b128 v[210:213], v183 offset:22528
	ds_read_b128 v[214:217], v183 offset:23552
	global_load_lds_dwordx4 v[178:179], off
	s_add_i32 m0, s72, 0x2000
	v_lshl_add_u64 v[218:219], s[70:71], 0, v[154:155]
	s_add_u32 s70, s70, s14
	s_addc_u32 s71, s71, s15
	s_add_i32 s53, s53, s87
	global_load_lds_dwordx4 v[218:219], off
	v_lshl_add_u64 v[220:221], s[70:71], 0, v[150:151]
	s_mov_b32 m0, s53
	v_lshl_add_u64 v[222:223], s[70:71], 0, v[154:155]
	global_load_lds_dwordx4 v[220:221], off
	s_add_i32 m0, s53, 0x2000
	v_lshl_add_u64 v[224:225], s[28:29], 0, v[148:149]
	global_load_lds_dwordx4 v[222:223], off
	s_mov_b32 m0, s90
	v_lshl_add_u64 v[226:227], s[28:29], 0, v[152:153]
	global_load_lds_dwordx4 v[224:225], off
	s_mov_b32 m0, s91
	s_nop 0
	global_load_lds_dwordx4 v[226:227], off
	s_waitcnt vmcnt(8)
	s_waitcnt lgkmcnt(0)
	s_barrier
	s_waitcnt lgkmcnt(0)
	v_mfma_f32_16x16x32_bf16 v[48:51], v[130:133], v[186:189], v[48:51]
	v_mfma_f32_16x16x32_bf16 v[56:59], v[138:141], v[186:189], v[56:59]
	v_mfma_f32_16x16x32_bf16 v[32:35], v[130:133], v[194:197], v[32:35]
	v_mfma_f32_16x16x32_bf16 v[40:43], v[138:141], v[194:197], v[40:43]
	v_mfma_f32_16x16x32_bf16 v[16:19], v[130:133], v[202:205], v[16:19]
	v_mfma_f32_16x16x32_bf16 v[24:27], v[138:141], v[202:205], v[24:27]
	v_mfma_f32_16x16x32_bf16 v[0:3], v[130:133], v[210:213], v[0:3]
	v_mfma_f32_16x16x32_bf16 v[12:15], v[138:141], v[210:213], v[12:15]
	v_mfma_f32_16x16x32_bf16 v[48:51], v[134:137], v[190:193], v[48:51]
	v_mfma_f32_16x16x32_bf16 v[56:59], v[142:145], v[190:193], v[56:59]
	v_mfma_f32_16x16x32_bf16 v[32:35], v[134:137], v[198:201], v[32:35]
	v_mfma_f32_16x16x32_bf16 v[40:43], v[142:145], v[198:201], v[40:43]
	v_mfma_f32_16x16x32_bf16 v[16:19], v[134:137], v[206:209], v[16:19]
	v_mfma_f32_16x16x32_bf16 v[24:27], v[142:145], v[206:209], v[24:27]
	v_mfma_f32_16x16x32_bf16 v[0:3], v[134:137], v[214:217], v[0:3]
	v_mfma_f32_16x16x32_bf16 v[12:15], v[142:145], v[214:217], v[12:15]
	v_mfma_f32_16x16x32_bf16 v[52:55], v[162:165], v[186:189], v[52:55]
	v_mfma_f32_16x16x32_bf16 v[60:63], v[170:173], v[186:189], v[60:63]
	v_mfma_f32_16x16x32_bf16 v[36:39], v[162:165], v[194:197], v[36:39]
	v_mfma_f32_16x16x32_bf16 v[44:47], v[170:173], v[194:197], v[44:47]
	v_mfma_f32_16x16x32_bf16 v[20:23], v[162:165], v[202:205], v[20:23]
	v_mfma_f32_16x16x32_bf16 v[28:31], v[170:173], v[202:205], v[28:31]
	v_mfma_f32_16x16x32_bf16 v[4:7], v[162:165], v[210:213], v[4:7]
	v_mfma_f32_16x16x32_bf16 v[8:11], v[170:173], v[210:213], v[8:11]
	v_mfma_f32_16x16x32_bf16 v[52:55], v[166:169], v[190:193], v[52:55]
	v_mfma_f32_16x16x32_bf16 v[60:63], v[174:177], v[190:193], v[60:63]
	v_mfma_f32_16x16x32_bf16 v[36:39], v[166:169], v[198:201], v[36:39]
	v_mfma_f32_16x16x32_bf16 v[44:47], v[174:177], v[198:201], v[44:47]
	v_mfma_f32_16x16x32_bf16 v[20:23], v[166:169], v[206:209], v[20:23]
	v_mfma_f32_16x16x32_bf16 v[28:31], v[174:177], v[206:209], v[28:31]
	v_mfma_f32_16x16x32_bf16 v[4:7], v[166:169], v[214:217], v[4:7]
	v_mfma_f32_16x16x32_bf16 v[8:11], v[174:177], v[214:217], v[8:11]
	s_barrier
	s_add_i32 s53, 0, 0x18000
	v_add_u32_e32 v128, s53, v181
	s_add_i32 s70, 0, 0x1c000
	ds_read_b128 v[130:133], v128
	ds_read_b128 v[134:137], v128 offset:1024
	ds_read_b128 v[138:141], v128 offset:2048
	ds_read_b128 v[142:145], v128 offset:3072
	v_add_u32_e32 v128, s70, v181
	ds_read_b128 v[162:165], v128
	ds_read_b128 v[166:169], v128 offset:1024
	ds_read_b128 v[170:173], v128 offset:2048
	ds_read_b128 v[174:177], v128 offset:3072
	s_add_u32 s28, s28, s14
	s_addc_u32 s29, s29, s15
	s_mov_b32 m0, s92
	v_lshl_add_u64 v[228:229], s[28:29], 0, v[148:149]
	ds_read_b128 v[186:189], v183 offset:32768
	ds_read_b128 v[190:193], v183 offset:33792
	ds_read_b128 v[194:197], v183 offset:34816
	ds_read_b128 v[198:201], v183 offset:35840
	ds_read_b128 v[202:205], v183 offset:36864
	ds_read_b128 v[206:209], v183 offset:37888
	ds_read_b128 v[210:213], v183 offset:38912
	ds_read_b128 v[214:217], v183 offset:39936
	global_load_lds_dwordx4 v[228:229], off
	v_lshl_add_u64 v[228:229], s[28:29], 0, v[152:153]
	s_mov_b32 m0, s93
	s_nop 0
	global_load_lds_dwordx4 v[228:229], off
	s_waitcnt vmcnt(8)
	s_waitcnt lgkmcnt(0)
	s_barrier
	s_waitcnt lgkmcnt(0)
	v_mfma_f32_16x16x32_bf16 v[112:115], v[130:133], v[186:189], v[112:115]
	v_mfma_f32_16x16x32_bf16 v[120:123], v[138:141], v[186:189], v[120:123]
	v_mfma_f32_16x16x32_bf16 v[96:99], v[130:133], v[194:197], v[96:99]
	v_mfma_f32_16x16x32_bf16 v[104:107], v[138:141], v[194:197], v[104:107]
	v_mfma_f32_16x16x32_bf16 v[80:83], v[130:133], v[202:205], v[80:83]
	v_mfma_f32_16x16x32_bf16 v[88:91], v[138:141], v[202:205], v[88:91]
	v_mfma_f32_16x16x32_bf16 v[64:67], v[130:133], v[210:213], v[64:67]
	v_mfma_f32_16x16x32_bf16 v[72:75], v[138:141], v[210:213], v[72:75]
	v_mfma_f32_16x16x32_bf16 v[112:115], v[134:137], v[190:193], v[112:115]
	v_mfma_f32_16x16x32_bf16 v[120:123], v[142:145], v[190:193], v[120:123]
	v_mfma_f32_16x16x32_bf16 v[96:99], v[134:137], v[198:201], v[96:99]
	v_mfma_f32_16x16x32_bf16 v[104:107], v[142:145], v[198:201], v[104:107]
	v_mfma_f32_16x16x32_bf16 v[80:83], v[134:137], v[206:209], v[80:83]
	v_mfma_f32_16x16x32_bf16 v[88:91], v[142:145], v[206:209], v[88:91]
	v_mfma_f32_16x16x32_bf16 v[64:67], v[134:137], v[214:217], v[64:67]
	v_mfma_f32_16x16x32_bf16 v[72:75], v[142:145], v[214:217], v[72:75]
	v_mfma_f32_16x16x32_bf16 v[116:119], v[162:165], v[186:189], v[116:119]
	v_mfma_f32_16x16x32_bf16 v[124:127], v[170:173], v[186:189], v[124:127]
	v_mfma_f32_16x16x32_bf16 v[100:103], v[162:165], v[194:197], v[100:103]
	v_mfma_f32_16x16x32_bf16 v[108:111], v[170:173], v[194:197], v[108:111]
	v_mfma_f32_16x16x32_bf16 v[84:87], v[162:165], v[202:205], v[84:87]
	v_mfma_f32_16x16x32_bf16 v[92:95], v[170:173], v[202:205], v[92:95]
	v_mfma_f32_16x16x32_bf16 v[68:71], v[162:165], v[210:213], v[68:71]
	v_mfma_f32_16x16x32_bf16 v[76:79], v[170:173], v[210:213], v[76:79]
	v_mfma_f32_16x16x32_bf16 v[116:119], v[166:169], v[190:193], v[116:119]
	v_mfma_f32_16x16x32_bf16 v[124:127], v[174:177], v[190:193], v[124:127]
	v_mfma_f32_16x16x32_bf16 v[100:103], v[166:169], v[198:201], v[100:103]
	v_mfma_f32_16x16x32_bf16 v[108:111], v[174:177], v[198:201], v[108:111]
	v_mfma_f32_16x16x32_bf16 v[84:87], v[166:169], v[206:209], v[84:87]
	v_mfma_f32_16x16x32_bf16 v[92:95], v[174:177], v[206:209], v[92:95]
	v_mfma_f32_16x16x32_bf16 v[68:71], v[166:169], v[214:217], v[68:71]
	v_mfma_f32_16x16x32_bf16 v[76:79], v[174:177], v[214:217], v[76:79]
	s_barrier
	s_add_i32 s28, s53, s87
	v_lshl_add_u64 v[178:179], v[178:179], 0, s[34:35]
	s_mov_b32 m0, s28
	ds_read_b128 v[186:189], v183 offset:49152
	ds_read_b128 v[190:193], v183 offset:50176
	ds_read_b128 v[194:197], v183 offset:51200
	ds_read_b128 v[198:201], v183 offset:52224
	ds_read_b128 v[202:205], v183 offset:53248
	ds_read_b128 v[206:209], v183 offset:54272
	ds_read_b128 v[210:213], v183 offset:55296
	ds_read_b128 v[214:217], v183 offset:56320
	global_load_lds_dwordx4 v[178:179], off
	v_lshl_add_u64 v[178:179], v[218:219], 0, s[34:35]
	s_add_i32 m0, s28, 0x2000
	s_add_i32 s28, s70, s87
	global_load_lds_dwordx4 v[178:179], off
	v_lshl_add_u64 v[178:179], v[220:221], 0, s[34:35]
	s_mov_b32 m0, s28
	s_nop 0
	global_load_lds_dwordx4 v[178:179], off
	v_lshl_add_u64 v[178:179], v[222:223], 0, s[34:35]
	s_add_i32 m0, s28, 0x2000
	s_nop 0
	global_load_lds_dwordx4 v[178:179], off
	v_lshl_add_u64 v[178:179], v[224:225], 0, s[34:35]
	s_mov_b32 m0, s97
	s_nop 0
	global_load_lds_dwordx4 v[178:179], off
	v_lshl_add_u64 v[178:179], v[226:227], 0, s[34:35]
	s_mov_b32 m0, s48
	s_nop 0
	global_load_lds_dwordx4 v[178:179], off
	s_waitcnt vmcnt(8)
	s_waitcnt lgkmcnt(0)
	s_barrier
	s_waitcnt lgkmcnt(0)
	v_mfma_f32_16x16x32_bf16 v[48:51], v[130:133], v[186:189], v[48:51]
	v_mfma_f32_16x16x32_bf16 v[56:59], v[138:141], v[186:189], v[56:59]
	v_mfma_f32_16x16x32_bf16 v[32:35], v[130:133], v[194:197], v[32:35]
	v_mfma_f32_16x16x32_bf16 v[40:43], v[138:141], v[194:197], v[40:43]
	v_mfma_f32_16x16x32_bf16 v[16:19], v[130:133], v[202:205], v[16:19]
	v_mfma_f32_16x16x32_bf16 v[24:27], v[138:141], v[202:205], v[24:27]
	v_mfma_f32_16x16x32_bf16 v[0:3], v[130:133], v[210:213], v[0:3]
	v_mfma_f32_16x16x32_bf16 v[12:15], v[138:141], v[210:213], v[12:15]
	v_mfma_f32_16x16x32_bf16 v[48:51], v[134:137], v[190:193], v[48:51]
	v_mfma_f32_16x16x32_bf16 v[56:59], v[142:145], v[190:193], v[56:59]
	v_mfma_f32_16x16x32_bf16 v[32:35], v[134:137], v[198:201], v[32:35]
	v_mfma_f32_16x16x32_bf16 v[40:43], v[142:145], v[198:201], v[40:43]
	v_mfma_f32_16x16x32_bf16 v[16:19], v[134:137], v[206:209], v[16:19]
	v_mfma_f32_16x16x32_bf16 v[24:27], v[142:145], v[206:209], v[24:27]
	v_mfma_f32_16x16x32_bf16 v[0:3], v[134:137], v[214:217], v[0:3]
	v_mfma_f32_16x16x32_bf16 v[12:15], v[142:145], v[214:217], v[12:15]
	v_mfma_f32_16x16x32_bf16 v[52:55], v[162:165], v[186:189], v[52:55]
	v_mfma_f32_16x16x32_bf16 v[60:63], v[170:173], v[186:189], v[60:63]
	v_mfma_f32_16x16x32_bf16 v[36:39], v[162:165], v[194:197], v[36:39]
	v_mfma_f32_16x16x32_bf16 v[44:47], v[170:173], v[194:197], v[44:47]
	v_mfma_f32_16x16x32_bf16 v[20:23], v[162:165], v[202:205], v[20:23]
	v_mfma_f32_16x16x32_bf16 v[28:31], v[170:173], v[202:205], v[28:31]
	v_mfma_f32_16x16x32_bf16 v[4:7], v[162:165], v[210:213], v[4:7]
	v_mfma_f32_16x16x32_bf16 v[8:11], v[170:173], v[210:213], v[8:11]
	v_mfma_f32_16x16x32_bf16 v[52:55], v[166:169], v[190:193], v[52:55]
	v_mfma_f32_16x16x32_bf16 v[60:63], v[174:177], v[190:193], v[60:63]
	v_mfma_f32_16x16x32_bf16 v[36:39], v[166:169], v[198:201], v[36:39]
	v_mfma_f32_16x16x32_bf16 v[44:47], v[174:177], v[198:201], v[44:47]
	v_mfma_f32_16x16x32_bf16 v[20:23], v[166:169], v[206:209], v[20:23]
	v_mfma_f32_16x16x32_bf16 v[28:31], v[174:177], v[206:209], v[28:31]
	v_mfma_f32_16x16x32_bf16 v[4:7], v[166:169], v[214:217], v[4:7]
	v_mfma_f32_16x16x32_bf16 v[8:11], v[174:177], v[214:217], v[8:11]
	s_barrier
	s_add_u32 s40, s40, 0x100
	s_addc_u32 s41, s41, 0
	s_add_u32 s33, s33, 0x100
	s_addc_u32 s42, s42, 0
	s_cmp_ge_i32 s43, s95
	s_mov_b32 s28, s43
	s_cbranch_scc0 .LBB0_293

.Lpro_1:
	s_mov_b32 s101, 0
	s_waitcnt vmcnt(8)
	s_barrier
	v_bfe_u32 v0, v146, 4, 2
	v_lshlrev_b32_e32 v2, 4, v0
	s_and_b32 s40, s38, 3
	s_ashr_i32 s57, s37, 6
	v_lshl_or_b32 v2, v147, 6, v2
	s_lshl_b32 s37, s39, 13
	v_and_b32_e32 v3, 32, v144
	v_bitop3_b32 v4, v2, s37, v3 bitop3:0xde
	s_lshl_b32 s37, s40, 12
	s_cmp_gt_i32 s36, 63
	v_bitop3_b32 v149, s37, v2, v3 bitop3:0xf6
	s_cselect_b64 s[36:37], -1, 0
	s_add_i32 s58, s57, -2
	v_lshl_or_b32 v148, s39, 6, v147
	v_lshlrev_b32_e32 v1, 3, v0
	s_cmpk_lt_u32 s33, 0x100
	v_cmp_eq_u32_e64 s[38:39], 0, v0
	v_add_u32_e32 v0, v14, v12
	s_waitcnt vmcnt(6)
	s_cselect_b64 s[44:45], -1, 0
	s_ashr_i32 s60, s4, 31
	s_ashr_i32 s61, s5, 31
	s_lshl_b32 s33, s40, 2
	v_add_lshl_u32 v128, v0, v13, 1
	v_add_u32_e32 v0, v17, v15
	s_add_u32 s62, s10, s33
	v_lshl_add_u64 v[138:139], s[22:23], 0, v[128:129]
	v_add_lshl_u32 v128, v0, v16, 1
	v_lshl_or_b32 v150, s40, 5, v1
	s_mov_b32 s59, 0
	s_addc_u32 s63, s11, 0
	v_lshl_add_u64 v[140:141], s[22:23], 0, v[128:129]
	v_add_u32_e32 v151, 0, v4
	s_barrier
	s_branch .LBB0_752

.LBB0_764:
	s_add_i32 s72, s28, 2
	s_add_u32 s73, s50, 0x80
	s_addc_u32 s29, s51, 0
	s_add_i32 s76, 0, 0x10000
	s_cmp_eq_u32 s58, s28
	s_cselect_b32 s29, s43, s29
	s_cselect_b32 s28, s42, s73
	v_add_u32_e32 v128, s76, v149
	s_cselect_b32 s87, s47, s71
	s_cselect_b32 s86, s46, s33
	s_add_i32 s73, 0, 0x14000
	ds_read_b128 v[152:155], v128
	ds_read_b128 v[156:159], v128 offset:1024
	ds_read_b128 v[160:163], v128 offset:2048
	ds_read_b128 v[164:167], v128 offset:3072
	v_add_u32_e32 v128, s73, v149
	ds_read_b128 v[168:171], v128
	ds_read_b128 v[172:175], v128 offset:1024
	ds_read_b128 v[176:179], v128 offset:2048
	ds_read_b128 v[180:183], v128 offset:3072
	v_lshl_add_u64 v[142:143], s[50:51], 0, v[138:139]
	s_add_i32 m0, s20, 0xc000
	ds_read_b128 v[184:187], v151
	ds_read_b128 v[188:191], v151 offset:1024
	ds_read_b128 v[192:195], v151 offset:2048
	ds_read_b128 v[196:199], v151 offset:3072
	ds_read_b128 v[200:203], v151 offset:4096
	ds_read_b128 v[204:207], v151 offset:5120
	ds_read_b128 v[208:211], v151 offset:6144
	ds_read_b128 v[212:215], v151 offset:7168
	global_load_lds_dwordx4 v[142:143], off
	v_lshl_add_u64 v[142:143], s[50:51], 0, v[140:141]
	s_add_i32 m0, s20, 0xe000
	s_nop 0
	global_load_lds_dwordx4 v[142:143], off
	s_cmp_eq_u32 s101, 0
	s_cbranch_scc1 .Lrx_strict_764_0
	s_waitcnt vmcnt(40)
	s_branch .Lrx_join_764_0

.Lrx_join_764_0:
	s_waitcnt lgkmcnt(0)
	s_barrier
	s_waitcnt lgkmcnt(0)
	v_mfma_f32_16x16x32_bf16 v[120:123], v[152:155], v[184:187], v[120:123]
	v_mfma_f32_16x16x32_bf16 v[124:127], v[160:163], v[184:187], v[124:127]
	v_mfma_f32_16x16x32_bf16 v[108:111], v[152:155], v[192:195], v[108:111]
	v_mfma_f32_16x16x32_bf16 v[104:107], v[160:163], v[192:195], v[104:107]
	v_mfma_f32_16x16x32_bf16 v[92:95], v[152:155], v[200:203], v[92:95]
	v_mfma_f32_16x16x32_bf16 v[88:91], v[160:163], v[200:203], v[88:91]
	v_mfma_f32_16x16x32_bf16 v[76:79], v[152:155], v[208:211], v[76:79]
	v_mfma_f32_16x16x32_bf16 v[72:75], v[160:163], v[208:211], v[72:75]
	v_mfma_f32_16x16x32_bf16 v[120:123], v[156:159], v[188:191], v[120:123]
	v_mfma_f32_16x16x32_bf16 v[124:127], v[164:167], v[188:191], v[124:127]
	v_mfma_f32_16x16x32_bf16 v[108:111], v[156:159], v[196:199], v[108:111]
	v_mfma_f32_16x16x32_bf16 v[104:107], v[164:167], v[196:199], v[104:107]
	v_mfma_f32_16x16x32_bf16 v[92:95], v[156:159], v[204:207], v[92:95]
	v_mfma_f32_16x16x32_bf16 v[88:91], v[164:167], v[204:207], v[88:91]
	v_mfma_f32_16x16x32_bf16 v[76:79], v[156:159], v[212:215], v[76:79]
	v_mfma_f32_16x16x32_bf16 v[72:75], v[164:167], v[212:215], v[72:75]
	v_mfma_f32_16x16x32_bf16 v[116:119], v[168:171], v[184:187], v[116:119]
	v_mfma_f32_16x16x32_bf16 v[112:115], v[176:179], v[184:187], v[112:115]
	v_mfma_f32_16x16x32_bf16 v[100:103], v[168:171], v[192:195], v[100:103]
	v_mfma_f32_16x16x32_bf16 v[96:99], v[176:179], v[192:195], v[96:99]
	v_mfma_f32_16x16x32_bf16 v[84:87], v[168:171], v[200:203], v[84:87]
	v_mfma_f32_16x16x32_bf16 v[80:83], v[176:179], v[200:203], v[80:83]
	v_mfma_f32_16x16x32_bf16 v[68:71], v[168:171], v[208:211], v[68:71]
	v_mfma_f32_16x16x32_bf16 v[64:67], v[176:179], v[208:211], v[64:67]
	v_mfma_f32_16x16x32_bf16 v[116:119], v[172:175], v[188:191], v[116:119]
	v_mfma_f32_16x16x32_bf16 v[112:115], v[180:183], v[188:191], v[112:115]
	v_mfma_f32_16x16x32_bf16 v[100:103], v[172:175], v[196:199], v[100:103]
	v_mfma_f32_16x16x32_bf16 v[96:99], v[180:183], v[196:199], v[96:99]
	v_mfma_f32_16x16x32_bf16 v[84:87], v[172:175], v[204:207], v[84:87]
	v_mfma_f32_16x16x32_bf16 v[80:83], v[180:183], v[204:207], v[80:83]
	v_mfma_f32_16x16x32_bf16 v[68:71], v[172:175], v[212:215], v[68:71]
	v_mfma_f32_16x16x32_bf16 v[64:67], v[180:183], v[212:215], v[64:67]
	s_barrier
	s_add_i32 s76, s76, s18
	v_lshl_add_u64 v[142:143], s[86:87], 0, v[132:133]
	s_mov_b32 m0, s76
	ds_read_b128 v[184:187], v151 offset:16384
	ds_read_b128 v[188:191], v151 offset:17408
	ds_read_b128 v[192:195], v151 offset:18432
	ds_read_b128 v[196:199], v151 offset:19456
	ds_read_b128 v[200:203], v151 offset:20480
	ds_read_b128 v[204:207], v151 offset:21504
	ds_read_b128 v[208:211], v151 offset:22528
	ds_read_b128 v[212:215], v151 offset:23552
	global_load_lds_dwordx4 v[142:143], off
	s_add_i32 m0, s76, 0x2000
	v_lshl_add_u64 v[216:217], s[86:87], 0, v[136:137]
	s_add_u32 s86, s86, s22
	s_addc_u32 s87, s87, s23
	s_add_i32 s73, s73, s18
	global_load_lds_dwordx4 v[216:217], off
	v_lshl_add_u64 v[218:219], s[86:87], 0, v[132:133]
	s_mov_b32 m0, s73
	v_lshl_add_u64 v[220:221], s[86:87], 0, v[136:137]
	global_load_lds_dwordx4 v[218:219], off
	s_add_i32 m0, s73, 0x2000
	v_lshl_add_u64 v[222:223], s[28:29], 0, v[130:131]
	global_load_lds_dwordx4 v[220:221], off
	s_mov_b32 m0, s20
	v_lshl_add_u64 v[224:225], s[28:29], 0, v[134:135]
	global_load_lds_dwordx4 v[222:223], off
	s_mov_b32 m0, s48
	s_nop 0
	global_load_lds_dwordx4 v[224:225], off
	s_cmp_eq_u32 s101, 0
	s_cbranch_scc1 .Lrx_strict_764_1
	s_waitcnt vmcnt(40)
	s_branch .Lrx_join_764_1

.Lrx_join_764_1:
	s_mov_b32 s101, 0
	s_waitcnt lgkmcnt(0)
	s_barrier
	s_waitcnt lgkmcnt(0)
	v_mfma_f32_16x16x32_bf16 v[60:63], v[152:155], v[184:187], v[60:63]
	v_mfma_f32_16x16x32_bf16 v[56:59], v[160:163], v[184:187], v[56:59]
	v_mfma_f32_16x16x32_bf16 v[44:47], v[152:155], v[192:195], v[44:47]
	v_mfma_f32_16x16x32_bf16 v[40:43], v[160:163], v[192:195], v[40:43]
	v_mfma_f32_16x16x32_bf16 v[28:31], v[152:155], v[200:203], v[28:31]
	v_mfma_f32_16x16x32_bf16 v[24:27], v[160:163], v[200:203], v[24:27]
	v_mfma_f32_16x16x32_bf16 v[12:15], v[152:155], v[208:211], v[12:15]
	v_mfma_f32_16x16x32_bf16 v[8:11], v[160:163], v[208:211], v[8:11]
	v_mfma_f32_16x16x32_bf16 v[60:63], v[156:159], v[188:191], v[60:63]
	v_mfma_f32_16x16x32_bf16 v[56:59], v[164:167], v[188:191], v[56:59]
	v_mfma_f32_16x16x32_bf16 v[44:47], v[156:159], v[196:199], v[44:47]
	v_mfma_f32_16x16x32_bf16 v[40:43], v[164:167], v[196:199], v[40:43]
	v_mfma_f32_16x16x32_bf16 v[28:31], v[156:159], v[204:207], v[28:31]
	v_mfma_f32_16x16x32_bf16 v[24:27], v[164:167], v[204:207], v[24:27]
	v_mfma_f32_16x16x32_bf16 v[12:15], v[156:159], v[212:215], v[12:15]
	v_mfma_f32_16x16x32_bf16 v[8:11], v[164:167], v[212:215], v[8:11]
	v_mfma_f32_16x16x32_bf16 v[52:55], v[168:171], v[184:187], v[52:55]
	v_mfma_f32_16x16x32_bf16 v[48:51], v[176:179], v[184:187], v[48:51]
	v_mfma_f32_16x16x32_bf16 v[36:39], v[168:171], v[192:195], v[36:39]
	v_mfma_f32_16x16x32_bf16 v[32:35], v[176:179], v[192:195], v[32:35]
	v_mfma_f32_16x16x32_bf16 v[20:23], v[168:171], v[200:203], v[20:23]
	v_mfma_f32_16x16x32_bf16 v[16:19], v[176:179], v[200:203], v[16:19]
	v_mfma_f32_16x16x32_bf16 v[4:7], v[168:171], v[208:211], v[4:7]
	v_mfma_f32_16x16x32_bf16 v[0:3], v[176:179], v[208:211], v[0:3]
	v_mfma_f32_16x16x32_bf16 v[52:55], v[172:175], v[188:191], v[52:55]
	v_mfma_f32_16x16x32_bf16 v[48:51], v[180:183], v[188:191], v[48:51]
	v_mfma_f32_16x16x32_bf16 v[36:39], v[172:175], v[196:199], v[36:39]
	v_mfma_f32_16x16x32_bf16 v[32:35], v[180:183], v[196:199], v[32:35]
	v_mfma_f32_16x16x32_bf16 v[20:23], v[172:175], v[204:207], v[20:23]
	v_mfma_f32_16x16x32_bf16 v[16:19], v[180:183], v[204:207], v[16:19]
	v_mfma_f32_16x16x32_bf16 v[4:7], v[172:175], v[212:215], v[4:7]
	v_mfma_f32_16x16x32_bf16 v[0:3], v[180:183], v[212:215], v[0:3]
	s_barrier
	s_add_i32 s73, 0, 0x18000
	v_add_u32_e32 v128, s73, v149
	s_add_i32 s76, 0, 0x1c000
	ds_read_b128 v[152:155], v128
	ds_read_b128 v[156:159], v128 offset:1024
	ds_read_b128 v[160:163], v128 offset:2048
	ds_read_b128 v[164:167], v128 offset:3072
	v_add_u32_e32 v128, s76, v149
	ds_read_b128 v[168:171], v128
	ds_read_b128 v[172:175], v128 offset:1024
	ds_read_b128 v[176:179], v128 offset:2048
	ds_read_b128 v[180:183], v128 offset:3072
	s_add_u32 s28, s28, s22
	s_addc_u32 s29, s29, s23
	s_mov_b32 m0, s49
	v_lshl_add_u64 v[226:227], s[28:29], 0, v[130:131]
	ds_read_b128 v[184:187], v151 offset:32768
	ds_read_b128 v[188:191], v151 offset:33792
	ds_read_b128 v[192:195], v151 offset:34816
	ds_read_b128 v[196:199], v151 offset:35840
	ds_read_b128 v[200:203], v151 offset:36864
	ds_read_b128 v[204:207], v151 offset:37888
	ds_read_b128 v[208:211], v151 offset:38912
	ds_read_b128 v[212:215], v151 offset:39936
	global_load_lds_dwordx4 v[226:227], off
	v_lshl_add_u64 v[226:227], s[28:29], 0, v[134:135]
	s_mov_b32 m0, s52
	s_nop 0
	global_load_lds_dwordx4 v[226:227], off
	s_waitcnt vmcnt(8)
	s_waitcnt lgkmcnt(0)
	s_barrier
	s_waitcnt lgkmcnt(0)
	v_mfma_f32_16x16x32_bf16 v[120:123], v[152:155], v[184:187], v[120:123]
	v_mfma_f32_16x16x32_bf16 v[124:127], v[160:163], v[184:187], v[124:127]
	v_mfma_f32_16x16x32_bf16 v[108:111], v[152:155], v[192:195], v[108:111]
	v_mfma_f32_16x16x32_bf16 v[104:107], v[160:163], v[192:195], v[104:107]
	v_mfma_f32_16x16x32_bf16 v[92:95], v[152:155], v[200:203], v[92:95]
	v_mfma_f32_16x16x32_bf16 v[88:91], v[160:163], v[200:203], v[88:91]
	v_mfma_f32_16x16x32_bf16 v[76:79], v[152:155], v[208:211], v[76:79]
	v_mfma_f32_16x16x32_bf16 v[72:75], v[160:163], v[208:211], v[72:75]
	v_mfma_f32_16x16x32_bf16 v[120:123], v[156:159], v[188:191], v[120:123]
	v_mfma_f32_16x16x32_bf16 v[124:127], v[164:167], v[188:191], v[124:127]
	v_mfma_f32_16x16x32_bf16 v[108:111], v[156:159], v[196:199], v[108:111]
	v_mfma_f32_16x16x32_bf16 v[104:107], v[164:167], v[196:199], v[104:107]
	v_mfma_f32_16x16x32_bf16 v[92:95], v[156:159], v[204:207], v[92:95]
	v_mfma_f32_16x16x32_bf16 v[88:91], v[164:167], v[204:207], v[88:91]
	v_mfma_f32_16x16x32_bf16 v[76:79], v[156:159], v[212:215], v[76:79]
	v_mfma_f32_16x16x32_bf16 v[72:75], v[164:167], v[212:215], v[72:75]
	v_mfma_f32_16x16x32_bf16 v[116:119], v[168:171], v[184:187], v[116:119]
	v_mfma_f32_16x16x32_bf16 v[112:115], v[176:179], v[184:187], v[112:115]
	v_mfma_f32_16x16x32_bf16 v[100:103], v[168:171], v[192:195], v[100:103]
	v_mfma_f32_16x16x32_bf16 v[96:99], v[176:179], v[192:195], v[96:99]
	v_mfma_f32_16x16x32_bf16 v[84:87], v[168:171], v[200:203], v[84:87]
	v_mfma_f32_16x16x32_bf16 v[80:83], v[176:179], v[200:203], v[80:83]
	v_mfma_f32_16x16x32_bf16 v[68:71], v[168:171], v[208:211], v[68:71]
	v_mfma_f32_16x16x32_bf16 v[64:67], v[176:179], v[208:211], v[64:67]
	v_mfma_f32_16x16x32_bf16 v[116:119], v[172:175], v[188:191], v[116:119]
	v_mfma_f32_16x16x32_bf16 v[112:115], v[180:183], v[188:191], v[112:115]
	v_mfma_f32_16x16x32_bf16 v[100:103], v[172:175], v[196:199], v[100:103]
	v_mfma_f32_16x16x32_bf16 v[96:99], v[180:183], v[196:199], v[96:99]
	v_mfma_f32_16x16x32_bf16 v[84:87], v[172:175], v[204:207], v[84:87]
	v_mfma_f32_16x16x32_bf16 v[80:83], v[180:183], v[204:207], v[80:83]
	v_mfma_f32_16x16x32_bf16 v[68:71], v[172:175], v[212:215], v[68:71]
	v_mfma_f32_16x16x32_bf16 v[64:67], v[180:183], v[212:215], v[64:67]
	s_barrier
	s_add_i32 s28, s73, s18
	v_lshl_add_u64 v[142:143], v[142:143], 0, s[34:35]
	s_mov_b32 m0, s28
	ds_read_b128 v[184:187], v151 offset:49152
	ds_read_b128 v[188:191], v151 offset:50176
	ds_read_b128 v[192:195], v151 offset:51200
	ds_read_b128 v[196:199], v151 offset:52224
	ds_read_b128 v[200:203], v151 offset:53248
	ds_read_b128 v[204:207], v151 offset:54272
	ds_read_b128 v[208:211], v151 offset:55296
	ds_read_b128 v[212:215], v151 offset:56320
	global_load_lds_dwordx4 v[142:143], off
	v_lshl_add_u64 v[142:143], v[216:217], 0, s[34:35]
	s_add_i32 m0, s28, 0x2000
	s_add_i32 s28, s76, s18
	global_load_lds_dwordx4 v[142:143], off
	v_lshl_add_u64 v[142:143], v[218:219], 0, s[34:35]
	s_mov_b32 m0, s28
	s_nop 0
	global_load_lds_dwordx4 v[142:143], off
	v_lshl_add_u64 v[142:143], v[220:221], 0, s[34:35]
	s_add_i32 m0, s28, 0x2000
	s_nop 0
	global_load_lds_dwordx4 v[142:143], off
	v_lshl_add_u64 v[142:143], v[222:223], 0, s[34:35]
	s_mov_b32 m0, s53
	s_nop 0
	global_load_lds_dwordx4 v[142:143], off
	v_lshl_add_u64 v[142:143], v[224:225], 0, s[34:35]
	s_mov_b32 m0, s56
	s_nop 0
	global_load_lds_dwordx4 v[142:143], off
	s_waitcnt vmcnt(8)
	s_waitcnt lgkmcnt(0)
	s_barrier
	s_waitcnt lgkmcnt(0)
	v_mfma_f32_16x16x32_bf16 v[60:63], v[152:155], v[184:187], v[60:63]
	v_mfma_f32_16x16x32_bf16 v[56:59], v[160:163], v[184:187], v[56:59]
	v_mfma_f32_16x16x32_bf16 v[44:47], v[152:155], v[192:195], v[44:47]
	v_mfma_f32_16x16x32_bf16 v[40:43], v[160:163], v[192:195], v[40:43]
	v_mfma_f32_16x16x32_bf16 v[28:31], v[152:155], v[200:203], v[28:31]
	v_mfma_f32_16x16x32_bf16 v[24:27], v[160:163], v[200:203], v[24:27]
	v_mfma_f32_16x16x32_bf16 v[12:15], v[152:155], v[208:211], v[12:15]
	v_mfma_f32_16x16x32_bf16 v[8:11], v[160:163], v[208:211], v[8:11]
	v_mfma_f32_16x16x32_bf16 v[60:63], v[156:159], v[188:191], v[60:63]
	v_mfma_f32_16x16x32_bf16 v[56:59], v[164:167], v[188:191], v[56:59]
	v_mfma_f32_16x16x32_bf16 v[44:47], v[156:159], v[196:199], v[44:47]
	v_mfma_f32_16x16x32_bf16 v[40:43], v[164:167], v[196:199], v[40:43]
	v_mfma_f32_16x16x32_bf16 v[28:31], v[156:159], v[204:207], v[28:31]
	v_mfma_f32_16x16x32_bf16 v[24:27], v[164:167], v[204:207], v[24:27]
	v_mfma_f32_16x16x32_bf16 v[12:15], v[156:159], v[212:215], v[12:15]
	v_mfma_f32_16x16x32_bf16 v[8:11], v[164:167], v[212:215], v[8:11]
	v_mfma_f32_16x16x32_bf16 v[52:55], v[168:171], v[184:187], v[52:55]
	v_mfma_f32_16x16x32_bf16 v[48:51], v[176:179], v[184:187], v[48:51]
	v_mfma_f32_16x16x32_bf16 v[36:39], v[168:171], v[192:195], v[36:39]
	v_mfma_f32_16x16x32_bf16 v[32:35], v[176:179], v[192:195], v[32:35]
	v_mfma_f32_16x16x32_bf16 v[20:23], v[168:171], v[200:203], v[20:23]
	v_mfma_f32_16x16x32_bf16 v[16:19], v[176:179], v[200:203], v[16:19]
	v_mfma_f32_16x16x32_bf16 v[4:7], v[168:171], v[208:211], v[4:7]
	v_mfma_f32_16x16x32_bf16 v[0:3], v[176:179], v[208:211], v[0:3]
	v_mfma_f32_16x16x32_bf16 v[52:55], v[172:175], v[188:191], v[52:55]
	v_mfma_f32_16x16x32_bf16 v[48:51], v[180:183], v[188:191], v[48:51]
	v_mfma_f32_16x16x32_bf16 v[36:39], v[172:175], v[196:199], v[36:39]
	v_mfma_f32_16x16x32_bf16 v[32:35], v[180:183], v[196:199], v[32:35]
	v_mfma_f32_16x16x32_bf16 v[20:23], v[172:175], v[204:207], v[20:23]
	v_mfma_f32_16x16x32_bf16 v[16:19], v[180:183], v[204:207], v[16:19]
	v_mfma_f32_16x16x32_bf16 v[4:7], v[172:175], v[212:215], v[4:7]
	v_mfma_f32_16x16x32_bf16 v[0:3], v[180:183], v[212:215], v[0:3]
	s_barrier
	s_add_u32 s50, s50, 0x100
	s_addc_u32 s51, s51, 0
	s_add_u32 s33, s33, 0x100
	s_addc_u32 s71, s71, 0
	s_cmp_ge_i32 s72, s57
	s_mov_b32 s28, s72
	s_cbranch_scc0 .LBB0_764
	s_mov_b32 s101, 1
	v_readlane_b32 s86, v255, 23
	v_readlane_b32 s87, v255, 24
	s_movk_i32 s76, 0x6000

.LBB0_899:
	s_add_i32 s33, s28, 2
	s_add_u32 s44, s42, 0x80
	s_addc_u32 s29, s43, 0
	s_add_i32 s46, 0, 0x10000
	s_cmp_eq_u32 s73, s28
	s_cselect_b32 s29, s71, s29
	s_cselect_b32 s28, s70, s44
	s_cselect_b32 s45, s27, s18
	s_cselect_b32 s44, s26, s7
	s_add_i32 s47, 0, 0x14000
	v_add_u32_e32 v40, s46, v181
	v_add_u32_e32 v170, s47, v181
	ds_read_b128 v[16:19], v40
	ds_read_b128 v[20:23], v40 offset:1024
	ds_read_b128 v[32:35], v40 offset:2048
	ds_read_b128 v[40:43], v40 offset:3072
	ds_read_b128 v[146:149], v170
	ds_read_b128 v[162:165], v170 offset:1024
	ds_read_b128 v[166:169], v170 offset:2048
	ds_read_b128 v[170:173], v170 offset:3072
	v_lshl_add_u64 v[214:215], s[42:43], 0, v[158:159]
	s_add_i32 m0, s86, 0xc000
	ds_read_b128 v[174:177], v184
	ds_read_b128 v[186:189], v184 offset:1024
	ds_read_b128 v[190:193], v184 offset:2048
	ds_read_b128 v[194:197], v184 offset:3072
	ds_read_b128 v[198:201], v184 offset:4096
	ds_read_b128 v[202:205], v184 offset:5120
	ds_read_b128 v[206:209], v184 offset:6144
	ds_read_b128 v[210:213], v184 offset:7168
	global_load_lds_dwordx4 v[214:215], off
	v_lshl_add_u64 v[214:215], s[42:43], 0, v[160:161]
	s_add_i32 m0, s86, 0xe000
	s_nop 0
	global_load_lds_dwordx4 v[214:215], off
	s_waitcnt vmcnt(8)
	s_waitcnt lgkmcnt(0)
	s_barrier
	s_waitcnt lgkmcnt(0)
	v_mfma_f32_16x16x32_bf16 v[138:141], v[16:19], v[174:177], v[138:141]
	v_mfma_f32_16x16x32_bf16 v[142:145], v[32:35], v[174:177], v[142:145]
	v_mfma_f32_16x16x32_bf16 v[124:127], v[16:19], v[190:193], v[124:127]
	v_mfma_f32_16x16x32_bf16 v[120:123], v[32:35], v[190:193], v[120:123]
	v_mfma_f32_16x16x32_bf16 v[108:111], v[16:19], v[198:201], v[108:111]
	v_mfma_f32_16x16x32_bf16 v[104:107], v[32:35], v[198:201], v[104:107]
	v_mfma_f32_16x16x32_bf16 v[92:95], v[16:19], v[206:209], v[92:95]
	v_mfma_f32_16x16x32_bf16 v[88:91], v[32:35], v[206:209], v[88:91]
	v_mfma_f32_16x16x32_bf16 v[138:141], v[20:23], v[186:189], v[138:141]
	v_mfma_f32_16x16x32_bf16 v[142:145], v[40:43], v[186:189], v[142:145]
	v_mfma_f32_16x16x32_bf16 v[124:127], v[20:23], v[194:197], v[124:127]
	v_mfma_f32_16x16x32_bf16 v[120:123], v[40:43], v[194:197], v[120:123]
	v_mfma_f32_16x16x32_bf16 v[108:111], v[20:23], v[202:205], v[108:111]
	v_mfma_f32_16x16x32_bf16 v[104:107], v[40:43], v[202:205], v[104:107]
	v_mfma_f32_16x16x32_bf16 v[92:95], v[20:23], v[210:213], v[92:95]
	v_mfma_f32_16x16x32_bf16 v[88:91], v[40:43], v[210:213], v[88:91]
	v_mfma_f32_16x16x32_bf16 v[134:137], v[146:149], v[174:177], v[134:137]
	v_mfma_f32_16x16x32_bf16 v[130:133], v[166:169], v[174:177], v[130:133]
	v_mfma_f32_16x16x32_bf16 v[116:119], v[146:149], v[190:193], v[116:119]
	v_mfma_f32_16x16x32_bf16 v[112:115], v[166:169], v[190:193], v[112:115]
	v_mfma_f32_16x16x32_bf16 v[100:103], v[146:149], v[198:201], v[100:103]
	v_mfma_f32_16x16x32_bf16 v[96:99], v[166:169], v[198:201], v[96:99]
	v_mfma_f32_16x16x32_bf16 v[84:87], v[146:149], v[206:209], v[84:87]
	v_mfma_f32_16x16x32_bf16 v[80:83], v[166:169], v[206:209], v[80:83]
	v_mfma_f32_16x16x32_bf16 v[134:137], v[162:165], v[186:189], v[134:137]
	v_mfma_f32_16x16x32_bf16 v[130:133], v[170:173], v[186:189], v[130:133]
	v_mfma_f32_16x16x32_bf16 v[116:119], v[162:165], v[194:197], v[116:119]
	v_mfma_f32_16x16x32_bf16 v[112:115], v[170:173], v[194:197], v[112:115]
	v_mfma_f32_16x16x32_bf16 v[100:103], v[162:165], v[202:205], v[100:103]
	v_mfma_f32_16x16x32_bf16 v[96:99], v[170:173], v[202:205], v[96:99]
	v_mfma_f32_16x16x32_bf16 v[84:87], v[162:165], v[210:213], v[84:87]
	v_mfma_f32_16x16x32_bf16 v[80:83], v[170:173], v[210:213], v[80:83]
	s_barrier
	s_add_i32 s46, s46, s67
	v_lshl_add_u64 v[214:215], s[44:45], 0, v[128:129]
	s_mov_b32 m0, s46
	ds_read_b128 v[174:177], v184 offset:16384
	ds_read_b128 v[186:189], v184 offset:17408
	ds_read_b128 v[190:193], v184 offset:18432
	ds_read_b128 v[194:197], v184 offset:19456
	ds_read_b128 v[198:201], v184 offset:20480
	ds_read_b128 v[202:205], v184 offset:21504
	ds_read_b128 v[206:209], v184 offset:22528
	ds_read_b128 v[210:213], v184 offset:23552
	global_load_lds_dwordx4 v[214:215], off
	s_add_i32 m0, s46, 0x2000
	v_lshl_add_u64 v[216:217], s[44:45], 0, v[154:155]
	s_add_u32 s44, s44, s2
	s_addc_u32 s45, s45, s3
	s_add_i32 s46, s47, s67
	global_load_lds_dwordx4 v[216:217], off
	v_lshl_add_u64 v[218:219], s[44:45], 0, v[128:129]
	s_mov_b32 m0, s46
	v_lshl_add_u64 v[220:221], s[44:45], 0, v[154:155]
	global_load_lds_dwordx4 v[218:219], off
	s_add_i32 m0, s46, 0x2000
	v_lshl_add_u64 v[222:223], s[28:29], 0, v[150:151]
	global_load_lds_dwordx4 v[220:221], off
	s_mov_b32 m0, s86
	v_lshl_add_u64 v[224:225], s[28:29], 0, v[152:153]
	global_load_lds_dwordx4 v[222:223], off
	s_mov_b32 m0, s87
	s_nop 0
	global_load_lds_dwordx4 v[224:225], off
	s_waitcnt vmcnt(8)
	s_waitcnt lgkmcnt(0)
	s_barrier
	s_waitcnt lgkmcnt(0)
	v_mfma_f32_16x16x32_bf16 v[76:79], v[16:19], v[174:177], v[76:79]
	v_mfma_f32_16x16x32_bf16 v[72:75], v[32:35], v[174:177], v[72:75]
	v_mfma_f32_16x16x32_bf16 v[60:63], v[16:19], v[190:193], v[60:63]
	v_mfma_f32_16x16x32_bf16 v[56:59], v[32:35], v[190:193], v[56:59]
	v_mfma_f32_16x16x32_bf16 v[44:47], v[16:19], v[198:201], v[44:47]
	v_mfma_f32_16x16x32_bf16 v[36:39], v[32:35], v[198:201], v[36:39]
	v_mfma_f32_16x16x32_bf16 v[12:15], v[16:19], v[206:209], v[12:15]
	v_mfma_f32_16x16x32_bf16 v[8:11], v[32:35], v[206:209], v[8:11]
	v_mfma_f32_16x16x32_bf16 v[76:79], v[20:23], v[186:189], v[76:79]
	v_mfma_f32_16x16x32_bf16 v[72:75], v[40:43], v[186:189], v[72:75]
	v_mfma_f32_16x16x32_bf16 v[60:63], v[20:23], v[194:197], v[60:63]
	v_mfma_f32_16x16x32_bf16 v[56:59], v[40:43], v[194:197], v[56:59]
	v_mfma_f32_16x16x32_bf16 v[44:47], v[20:23], v[202:205], v[44:47]
	v_mfma_f32_16x16x32_bf16 v[36:39], v[40:43], v[202:205], v[36:39]
	v_mfma_f32_16x16x32_bf16 v[12:15], v[20:23], v[210:213], v[12:15]
	v_mfma_f32_16x16x32_bf16 v[8:11], v[40:43], v[210:213], v[8:11]
	v_mfma_f32_16x16x32_bf16 v[28:31], v[146:149], v[198:201], v[28:31]
	v_mfma_f32_16x16x32_bf16 v[24:27], v[166:169], v[198:201], v[24:27]
	v_mfma_f32_16x16x32_bf16 v[4:7], v[146:149], v[206:209], v[4:7]
	v_mfma_f32_16x16x32_bf16 v[0:3], v[166:169], v[206:209], v[0:3]
	v_mfma_f32_16x16x32_bf16 v[16:19], v[146:149], v[174:177], v[68:71]
	v_mfma_f32_16x16x32_bf16 v[20:23], v[166:169], v[174:177], v[64:67]
	v_mfma_f32_16x16x32_bf16 v[32:35], v[146:149], v[190:193], v[52:55]
	v_mfma_f32_16x16x32_bf16 v[40:43], v[166:169], v[190:193], v[48:51]
	v_mfma_f32_16x16x32_bf16 v[28:31], v[162:165], v[202:205], v[28:31]
	v_mfma_f32_16x16x32_bf16 v[24:27], v[170:173], v[202:205], v[24:27]
	v_mfma_f32_16x16x32_bf16 v[4:7], v[162:165], v[210:213], v[4:7]
	v_mfma_f32_16x16x32_bf16 v[0:3], v[170:173], v[210:213], v[0:3]
	v_mfma_f32_16x16x32_bf16 v[16:19], v[162:165], v[186:189], v[16:19]
	v_mfma_f32_16x16x32_bf16 v[20:23], v[170:173], v[186:189], v[20:23]
	v_mfma_f32_16x16x32_bf16 v[32:35], v[162:165], v[194:197], v[32:35]
	v_mfma_f32_16x16x32_bf16 v[40:43], v[170:173], v[194:197], v[40:43]
	s_barrier
	s_add_i32 s44, 0, 0x18000
	s_add_i32 s45, 0, 0x1c000
	v_add_u32_e32 v68, s44, v181
	v_add_u32_e32 v170, s45, v181
	ds_read_b128 v[48:51], v68
	ds_read_b128 v[52:55], v68 offset:1024
	ds_read_b128 v[64:67], v68 offset:2048
	ds_read_b128 v[68:71], v68 offset:3072
	ds_read_b128 v[146:149], v170
	ds_read_b128 v[162:165], v170 offset:1024
	ds_read_b128 v[166:169], v170 offset:2048
	ds_read_b128 v[170:173], v170 offset:3072
	s_add_u32 s28, s28, s2
	s_addc_u32 s29, s29, s3
	s_mov_b32 m0, s24
	v_lshl_add_u64 v[226:227], s[28:29], 0, v[150:151]
	ds_read_b128 v[174:177], v184 offset:32768
	ds_read_b128 v[186:189], v184 offset:33792
	ds_read_b128 v[190:193], v184 offset:34816
	ds_read_b128 v[194:197], v184 offset:35840
	ds_read_b128 v[198:201], v184 offset:36864
	ds_read_b128 v[202:205], v184 offset:37888
	ds_read_b128 v[206:209], v184 offset:38912
	ds_read_b128 v[210:213], v184 offset:39936
	global_load_lds_dwordx4 v[226:227], off
	v_lshl_add_u64 v[226:227], s[28:29], 0, v[152:153]
	s_mov_b32 m0, s25
	s_nop 0
	global_load_lds_dwordx4 v[226:227], off
	s_waitcnt vmcnt(8)
	s_waitcnt lgkmcnt(0)
	s_barrier
	s_waitcnt lgkmcnt(0)
	v_mfma_f32_16x16x32_bf16 v[138:141], v[48:51], v[174:177], v[138:141]
	v_mfma_f32_16x16x32_bf16 v[142:145], v[64:67], v[174:177], v[142:145]
	v_mfma_f32_16x16x32_bf16 v[124:127], v[48:51], v[190:193], v[124:127]
	v_mfma_f32_16x16x32_bf16 v[120:123], v[64:67], v[190:193], v[120:123]
	v_mfma_f32_16x16x32_bf16 v[108:111], v[48:51], v[198:201], v[108:111]
	v_mfma_f32_16x16x32_bf16 v[104:107], v[64:67], v[198:201], v[104:107]
	v_mfma_f32_16x16x32_bf16 v[92:95], v[48:51], v[206:209], v[92:95]
	v_mfma_f32_16x16x32_bf16 v[88:91], v[64:67], v[206:209], v[88:91]
	v_mfma_f32_16x16x32_bf16 v[138:141], v[52:55], v[186:189], v[138:141]
	v_mfma_f32_16x16x32_bf16 v[142:145], v[68:71], v[186:189], v[142:145]
	v_mfma_f32_16x16x32_bf16 v[124:127], v[52:55], v[194:197], v[124:127]
	v_mfma_f32_16x16x32_bf16 v[120:123], v[68:71], v[194:197], v[120:123]
	v_mfma_f32_16x16x32_bf16 v[108:111], v[52:55], v[202:205], v[108:111]
	v_mfma_f32_16x16x32_bf16 v[104:107], v[68:71], v[202:205], v[104:107]
	v_mfma_f32_16x16x32_bf16 v[92:95], v[52:55], v[210:213], v[92:95]
	v_mfma_f32_16x16x32_bf16 v[88:91], v[68:71], v[210:213], v[88:91]
	v_mfma_f32_16x16x32_bf16 v[134:137], v[146:149], v[174:177], v[134:137]
	v_mfma_f32_16x16x32_bf16 v[130:133], v[166:169], v[174:177], v[130:133]
	v_mfma_f32_16x16x32_bf16 v[116:119], v[146:149], v[190:193], v[116:119]
	v_mfma_f32_16x16x32_bf16 v[112:115], v[166:169], v[190:193], v[112:115]
	v_mfma_f32_16x16x32_bf16 v[100:103], v[146:149], v[198:201], v[100:103]
	v_mfma_f32_16x16x32_bf16 v[96:99], v[166:169], v[198:201], v[96:99]
	v_mfma_f32_16x16x32_bf16 v[84:87], v[146:149], v[206:209], v[84:87]
	v_mfma_f32_16x16x32_bf16 v[80:83], v[166:169], v[206:209], v[80:83]
	v_mfma_f32_16x16x32_bf16 v[134:137], v[162:165], v[186:189], v[134:137]
	v_mfma_f32_16x16x32_bf16 v[130:133], v[170:173], v[186:189], v[130:133]
	v_mfma_f32_16x16x32_bf16 v[116:119], v[162:165], v[194:197], v[116:119]
	v_mfma_f32_16x16x32_bf16 v[112:115], v[170:173], v[194:197], v[112:115]
	v_mfma_f32_16x16x32_bf16 v[100:103], v[162:165], v[202:205], v[100:103]
	v_mfma_f32_16x16x32_bf16 v[96:99], v[170:173], v[202:205], v[96:99]
	v_mfma_f32_16x16x32_bf16 v[84:87], v[162:165], v[210:213], v[84:87]
	v_mfma_f32_16x16x32_bf16 v[80:83], v[170:173], v[210:213], v[80:83]
	s_barrier
	s_add_i32 s28, s44, s67
	v_lshl_add_u64 v[214:215], v[214:215], 0, s[34:35]
	s_mov_b32 m0, s28
	ds_read_b128 v[174:177], v184 offset:49152
	ds_read_b128 v[186:189], v184 offset:50176
	ds_read_b128 v[190:193], v184 offset:51200
	ds_read_b128 v[194:197], v184 offset:52224
	ds_read_b128 v[198:201], v184 offset:53248
	ds_read_b128 v[202:205], v184 offset:54272
	ds_read_b128 v[206:209], v184 offset:55296
	ds_read_b128 v[210:213], v184 offset:56320
	global_load_lds_dwordx4 v[214:215], off
	v_lshl_add_u64 v[214:215], v[216:217], 0, s[34:35]
	s_add_i32 m0, s28, 0x2000
	s_add_i32 s28, s45, s67
	global_load_lds_dwordx4 v[214:215], off
	v_lshl_add_u64 v[214:215], v[218:219], 0, s[34:35]
	s_mov_b32 m0, s28
	s_nop 0
	global_load_lds_dwordx4 v[214:215], off
	v_lshl_add_u64 v[214:215], v[220:221], 0, s[34:35]
	s_add_i32 m0, s28, 0x2000
	s_nop 0
	global_load_lds_dwordx4 v[214:215], off
	v_lshl_add_u64 v[214:215], v[222:223], 0, s[34:35]
	s_mov_b32 m0, s88
	s_nop 0
	global_load_lds_dwordx4 v[214:215], off
	v_lshl_add_u64 v[214:215], v[224:225], 0, s[34:35]
	s_mov_b32 m0, s89
	s_nop 0
	global_load_lds_dwordx4 v[214:215], off
	s_waitcnt vmcnt(8)
	s_waitcnt lgkmcnt(0)
	s_barrier
	s_waitcnt lgkmcnt(0)
	v_mfma_f32_16x16x32_bf16 v[76:79], v[48:51], v[174:177], v[76:79]
	v_mfma_f32_16x16x32_bf16 v[72:75], v[64:67], v[174:177], v[72:75]
	v_mfma_f32_16x16x32_bf16 v[60:63], v[48:51], v[190:193], v[60:63]
	v_mfma_f32_16x16x32_bf16 v[56:59], v[64:67], v[190:193], v[56:59]
	v_mfma_f32_16x16x32_bf16 v[44:47], v[48:51], v[198:201], v[44:47]
	v_mfma_f32_16x16x32_bf16 v[36:39], v[64:67], v[198:201], v[36:39]
	v_mfma_f32_16x16x32_bf16 v[12:15], v[48:51], v[206:209], v[12:15]
	v_mfma_f32_16x16x32_bf16 v[8:11], v[64:67], v[206:209], v[8:11]
	v_mfma_f32_16x16x32_bf16 v[76:79], v[52:55], v[186:189], v[76:79]
	v_mfma_f32_16x16x32_bf16 v[72:75], v[68:71], v[186:189], v[72:75]
	v_mfma_f32_16x16x32_bf16 v[60:63], v[52:55], v[194:197], v[60:63]
	v_mfma_f32_16x16x32_bf16 v[56:59], v[68:71], v[194:197], v[56:59]
	v_mfma_f32_16x16x32_bf16 v[44:47], v[52:55], v[202:205], v[44:47]
	v_mfma_f32_16x16x32_bf16 v[36:39], v[68:71], v[202:205], v[36:39]
	v_mfma_f32_16x16x32_bf16 v[12:15], v[52:55], v[210:213], v[12:15]
	v_mfma_f32_16x16x32_bf16 v[8:11], v[68:71], v[210:213], v[8:11]
	v_mfma_f32_16x16x32_bf16 v[16:19], v[146:149], v[174:177], v[16:19]
	v_mfma_f32_16x16x32_bf16 v[68:71], v[162:165], v[186:189], v[16:19]
	v_mfma_f32_16x16x32_bf16 v[16:19], v[166:169], v[174:177], v[20:23]
	v_mfma_f32_16x16x32_bf16 v[64:67], v[170:173], v[186:189], v[16:19]
	v_mfma_f32_16x16x32_bf16 v[16:19], v[146:149], v[190:193], v[32:35]
	v_mfma_f32_16x16x32_bf16 v[52:55], v[162:165], v[194:197], v[16:19]
	v_mfma_f32_16x16x32_bf16 v[16:19], v[166:169], v[190:193], v[40:43]
	v_mfma_f32_16x16x32_bf16 v[48:51], v[170:173], v[194:197], v[16:19]
	v_mfma_f32_16x16x32_bf16 v[16:19], v[146:149], v[198:201], v[28:31]
	v_mfma_f32_16x16x32_bf16 v[28:31], v[162:165], v[202:205], v[16:19]
	v_mfma_f32_16x16x32_bf16 v[16:19], v[166:169], v[198:201], v[24:27]
	v_mfma_f32_16x16x32_bf16 v[4:7], v[146:149], v[206:209], v[4:7]
	v_mfma_f32_16x16x32_bf16 v[0:3], v[166:169], v[206:209], v[0:3]
	v_mfma_f32_16x16x32_bf16 v[24:27], v[170:173], v[202:205], v[16:19]
	v_mfma_f32_16x16x32_bf16 v[4:7], v[162:165], v[210:213], v[4:7]
	v_mfma_f32_16x16x32_bf16 v[0:3], v[170:173], v[210:213], v[0:3]
	s_barrier
	s_add_u32 s42, s42, 0x100
	s_addc_u32 s43, s43, 0
	s_add_u32 s7, s7, 0x100
	s_addc_u32 s18, s18, 0
	s_cmp_ge_i32 s33, s90
	s_mov_b32 s28, s33
	s_cbranch_scc0 .LBB0_899

.Lpro_3:
	s_mov_b32 s101, 0
	s_waitcnt vmcnt(8)
	s_barrier
	v_lshrrev_b32_e32 v6, 1, v196
	v_and_b32_e32 v6, 24, v6
	v_lshlrev_b32_e32 v7, 1, v6
	v_lshl_or_b32 v7, v197, 6, v7
	s_lshl_b32 s5, s5, 13
	v_and_b32_e32 v8, 32, v194
	s_lshr_b32 s33, s39, 26
	v_bitop3_b32 v9, v7, s5, v8 bitop3:0xde
	s_lshl_b32 s5, s18, 5
	s_add_i32 s33, s38, s33
	s_and_b32 s5, s5, 0x60
	s_ashr_i32 s49, s33, 6
	s_lshl_b32 s18, s5, 7
	s_cmp_gt_i32 s38, 63
	v_add_u32_e32 v0, v2, v0
	s_waitcnt vmcnt(6)
	s_cselect_b64 s[46:47], -1, 0
	s_add_i32 s70, s49, -2
	v_add_lshl_u32 v128, v0, v1, 1
	v_add_u32_e32 v0, v5, v3
	s_cmpk_lt_u32 s4, 0x100
	v_lshl_add_u64 v[182:183], s[36:37], 0, v[128:129]
	v_add_lshl_u32 v128, v0, v4, 1
	v_bitop3_b32 v203, s18, v7, v8 bitop3:0xf6
	s_cselect_b64 s[50:51], -1, 0
	s_ashr_i32 s71, s20, 31
	s_ashr_i32 s72, s60, 31
	v_or_b32_e32 v204, s5, v6
	v_lshl_add_u64 v[184:185], s[36:37], 0, v[128:129]
	s_mov_b32 s73, 0
	v_add_u32_e32 v205, 0, v9
	s_barrier
	s_branch .LBB0_1153

.LBB0_1165:
	s_add_i32 s52, s28, 2
	s_add_u32 s53, s58, 0x80
	s_addc_u32 s29, s59, 0
	s_add_i32 s76, 0, 0x10000
	s_cmp_eq_u32 s70, s28
	s_cselect_b32 s29, s41, s29
	s_cselect_b32 s28, s40, s53
	s_cselect_b32 s87, s57, s33
	s_cselect_b32 s86, s56, s18
	s_add_i32 s53, 0, 0x14000
	v_add_u32_e32 v76, s76, v203
	v_add_u32_e32 v124, s53, v203
	ds_read_b128 v[40:43], v76
	ds_read_b128 v[52:55], v76 offset:1024
	ds_read_b128 v[64:67], v76 offset:2048
	ds_read_b128 v[76:79], v76 offset:3072
	ds_read_b128 v[88:91], v124
	ds_read_b128 v[100:103], v124 offset:1024
	ds_read_b128 v[112:115], v124 offset:2048
	ds_read_b128 v[124:127], v124 offset:3072
	v_lshl_add_u64 v[214:215], s[58:59], 0, v[182:183]
	s_add_i32 m0, s62, 0xc000
	ds_read_b128 v[138:141], v205
	ds_read_b128 v[146:149], v205 offset:1024
	ds_read_b128 v[150:153], v205 offset:2048
	ds_read_b128 v[186:189], v205 offset:3072
	ds_read_b128 v[190:193], v205 offset:4096
	ds_read_b128 v[198:201], v205 offset:5120
	ds_read_b128 v[206:209], v205 offset:6144
	ds_read_b128 v[210:213], v205 offset:7168
	global_load_lds_dwordx4 v[214:215], off
	v_lshl_add_u64 v[214:215], s[58:59], 0, v[184:185]
	s_add_i32 m0, s62, 0xe000
	s_nop 0
	global_load_lds_dwordx4 v[214:215], off
	s_cmp_eq_u32 s101, 0
	s_cbranch_scc1 .Lrx_strict_1165_0
	s_waitcnt vmcnt(54)
	s_branch .Lrx_join_1165_0

.Lrx_join_1165_0:
	s_waitcnt lgkmcnt(0)
	s_barrier
	s_waitcnt lgkmcnt(0)
	v_mfma_f32_16x16x32_bf16 v[170:173], v[40:43], v[138:141], v[170:173]
	v_mfma_f32_16x16x32_bf16 v[72:75], v[64:67], v[138:141], v[72:75]
	v_mfma_f32_16x16x32_bf16 v[162:165], v[40:43], v[150:153], v[162:165]
	v_mfma_f32_16x16x32_bf16 v[60:63], v[64:67], v[150:153], v[60:63]
	v_mfma_f32_16x16x32_bf16 v[154:157], v[40:43], v[190:193], v[154:157]
	v_mfma_f32_16x16x32_bf16 v[48:51], v[64:67], v[190:193], v[48:51]
	v_mfma_f32_16x16x32_bf16 v[134:137], v[40:43], v[206:209], v[134:137]
	v_mfma_f32_16x16x32_bf16 v[36:39], v[64:67], v[206:209], v[36:39]
	v_mfma_f32_16x16x32_bf16 v[170:173], v[52:55], v[146:149], v[170:173]
	v_mfma_f32_16x16x32_bf16 v[72:75], v[76:79], v[146:149], v[72:75]
	v_mfma_f32_16x16x32_bf16 v[162:165], v[52:55], v[186:189], v[162:165]
	v_mfma_f32_16x16x32_bf16 v[60:63], v[76:79], v[186:189], v[60:63]
	v_mfma_f32_16x16x32_bf16 v[154:157], v[52:55], v[198:201], v[154:157]
	v_mfma_f32_16x16x32_bf16 v[48:51], v[76:79], v[198:201], v[48:51]
	v_mfma_f32_16x16x32_bf16 v[134:137], v[52:55], v[210:213], v[134:137]
	v_mfma_f32_16x16x32_bf16 v[36:39], v[76:79], v[210:213], v[36:39]
	v_mfma_f32_16x16x32_bf16 v[166:169], v[88:91], v[138:141], v[166:169]
	v_mfma_f32_16x16x32_bf16 v[68:71], v[112:115], v[138:141], v[68:71]
	v_mfma_f32_16x16x32_bf16 v[56:59], v[112:115], v[150:153], v[56:59]
	v_mfma_f32_16x16x32_bf16 v[142:145], v[88:91], v[190:193], v[142:145]
	v_mfma_f32_16x16x32_bf16 v[44:47], v[112:115], v[190:193], v[44:47]
	v_mfma_f32_16x16x32_bf16 v[130:133], v[88:91], v[206:209], v[130:133]
	v_mfma_f32_16x16x32_bf16 v[32:35], v[112:115], v[206:209], v[32:35]
	v_mfma_f32_16x16x32_bf16 v[166:169], v[100:103], v[146:149], v[166:169]
	v_mfma_f32_16x16x32_bf16 v[68:71], v[124:127], v[146:149], v[68:71]
	v_mfma_f32_16x16x32_bf16 v[138:141], v[88:91], v[150:153], v[158:161]
	v_mfma_f32_16x16x32_bf16 v[56:59], v[124:127], v[186:189], v[56:59]
	v_mfma_f32_16x16x32_bf16 v[142:145], v[100:103], v[198:201], v[142:145]
	v_mfma_f32_16x16x32_bf16 v[44:47], v[124:127], v[198:201], v[44:47]
	v_mfma_f32_16x16x32_bf16 v[130:133], v[100:103], v[210:213], v[130:133]
	v_mfma_f32_16x16x32_bf16 v[32:35], v[124:127], v[210:213], v[32:35]
	v_mfma_f32_16x16x32_bf16 v[138:141], v[100:103], v[186:189], v[138:141]
	s_barrier
	s_add_i32 s76, s76, s61
	v_lshl_add_u64 v[218:219], s[86:87], 0, v[176:177]
	s_mov_b32 m0, s76
	ds_read_b128 v[146:149], v205 offset:16384
	ds_read_b128 v[150:153], v205 offset:17408
	ds_read_b128 v[158:161], v205 offset:18432
	ds_read_b128 v[186:189], v205 offset:19456
	ds_read_b128 v[190:193], v205 offset:20480
	ds_read_b128 v[198:201], v205 offset:21504
	ds_read_b128 v[206:209], v205 offset:22528
	ds_read_b128 v[210:213], v205 offset:23552
	global_load_lds_dwordx4 v[218:219], off
	s_add_i32 m0, s76, 0x2000
	v_lshl_add_u64 v[220:221], s[86:87], 0, v[180:181]
	s_add_u32 s86, s86, s36
	s_addc_u32 s87, s87, s37
	s_add_i32 s53, s53, s61
	global_load_lds_dwordx4 v[220:221], off
	v_lshl_add_u64 v[222:223], s[86:87], 0, v[176:177]
	s_mov_b32 m0, s53
	v_lshl_add_u64 v[224:225], s[86:87], 0, v[180:181]
	global_load_lds_dwordx4 v[222:223], off
	s_add_i32 m0, s53, 0x2000
	v_lshl_add_u64 v[226:227], s[28:29], 0, v[174:175]
	global_load_lds_dwordx4 v[224:225], off
	s_mov_b32 m0, s62
	v_lshl_add_u64 v[228:229], s[28:29], 0, v[178:179]
	global_load_lds_dwordx4 v[226:227], off
	s_mov_b32 m0, s63
	s_nop 0
	global_load_lds_dwordx4 v[228:229], off
	s_cmp_eq_u32 s101, 0
	s_cbranch_scc1 .Lrx_strict_1165_1
	s_waitcnt vmcnt(54)
	s_branch .Lrx_join_1165_1

.Lrx_join_1165_1:
	s_mov_b32 s101, 0
	s_waitcnt lgkmcnt(0)
	s_barrier
	s_waitcnt lgkmcnt(0)
	v_mfma_f32_16x16x32_bf16 v[120:123], v[40:43], v[146:149], v[120:123]
	v_mfma_f32_16x16x32_bf16 v[28:31], v[64:67], v[146:149], v[28:31]
	v_mfma_f32_16x16x32_bf16 v[108:111], v[40:43], v[158:161], v[108:111]
	v_mfma_f32_16x16x32_bf16 v[20:23], v[64:67], v[158:161], v[20:23]
	v_mfma_f32_16x16x32_bf16 v[96:99], v[40:43], v[190:193], v[96:99]
	v_mfma_f32_16x16x32_bf16 v[12:15], v[64:67], v[190:193], v[12:15]
	v_mfma_f32_16x16x32_bf16 v[4:7], v[64:67], v[206:209], v[4:7]
	v_mfma_f32_16x16x32_bf16 v[120:123], v[52:55], v[150:153], v[120:123]
	v_mfma_f32_16x16x32_bf16 v[28:31], v[76:79], v[150:153], v[28:31]
	v_mfma_f32_16x16x32_bf16 v[108:111], v[52:55], v[186:189], v[108:111]
	v_mfma_f32_16x16x32_bf16 v[20:23], v[76:79], v[186:189], v[20:23]
	v_mfma_f32_16x16x32_bf16 v[96:99], v[52:55], v[198:201], v[96:99]
	v_mfma_f32_16x16x32_bf16 v[12:15], v[76:79], v[198:201], v[12:15]
	v_mfma_f32_16x16x32_bf16 v[40:43], v[40:43], v[206:209], v[84:87]
	v_mfma_f32_16x16x32_bf16 v[4:7], v[76:79], v[210:213], v[4:7]
	v_mfma_f32_16x16x32_bf16 v[40:43], v[52:55], v[210:213], v[40:43]
	v_mfma_f32_16x16x32_bf16 v[24:27], v[112:115], v[146:149], v[24:27]
	v_mfma_f32_16x16x32_bf16 v[16:19], v[112:115], v[158:161], v[16:19]
	v_mfma_f32_16x16x32_bf16 v[8:11], v[112:115], v[190:193], v[8:11]
	v_mfma_f32_16x16x32_bf16 v[80:83], v[88:91], v[206:209], v[80:83]
	v_mfma_f32_16x16x32_bf16 v[0:3], v[112:115], v[206:209], v[0:3]
	v_mfma_f32_16x16x32_bf16 v[52:55], v[88:91], v[146:149], v[116:119]
	v_mfma_f32_16x16x32_bf16 v[24:27], v[124:127], v[150:153], v[24:27]
	v_mfma_f32_16x16x32_bf16 v[64:67], v[88:91], v[158:161], v[104:107]
	v_mfma_f32_16x16x32_bf16 v[16:19], v[124:127], v[186:189], v[16:19]
	v_mfma_f32_16x16x32_bf16 v[76:79], v[88:91], v[190:193], v[92:95]
	v_mfma_f32_16x16x32_bf16 v[8:11], v[124:127], v[198:201], v[8:11]
	v_mfma_f32_16x16x32_bf16 v[80:83], v[100:103], v[210:213], v[80:83]
	v_mfma_f32_16x16x32_bf16 v[0:3], v[124:127], v[210:213], v[0:3]
	v_mfma_f32_16x16x32_bf16 v[52:55], v[100:103], v[150:153], v[52:55]
	v_mfma_f32_16x16x32_bf16 v[64:67], v[100:103], v[186:189], v[64:67]
	v_mfma_f32_16x16x32_bf16 v[76:79], v[100:103], v[198:201], v[76:79]
	s_barrier
	s_add_i32 s53, 0, 0x18000
	s_add_i32 s76, 0, 0x1c000
	v_add_u32_e32 v100, s53, v203
	v_add_u32_e32 v104, s76, v203
	ds_read_b128 v[84:87], v100
	ds_read_b128 v[88:91], v100 offset:1024
	ds_read_b128 v[92:95], v100 offset:2048
	ds_read_b128 v[100:103], v100 offset:3072
	ds_read_b128 v[112:115], v104
	ds_read_b128 v[124:127], v104 offset:1024
	ds_read_b128 v[146:149], v104 offset:2048
	ds_read_b128 v[150:153], v104 offset:3072
	s_add_u32 s28, s28, s36
	s_addc_u32 s29, s29, s37
	s_mov_b32 m0, s64
	v_lshl_add_u64 v[158:159], s[28:29], 0, v[174:175]
	ds_read_b128 v[104:107], v205 offset:32768
	ds_read_b128 v[116:119], v205 offset:33792
	ds_read_b128 v[186:189], v205 offset:34816
	ds_read_b128 v[190:193], v205 offset:35840
	ds_read_b128 v[198:201], v205 offset:36864
	ds_read_b128 v[206:209], v205 offset:37888
	ds_read_b128 v[210:213], v205 offset:38912
	ds_read_b128 v[214:217], v205 offset:39936
	global_load_lds_dwordx4 v[158:159], off
	v_lshl_add_u64 v[158:159], s[28:29], 0, v[178:179]
	s_mov_b32 m0, s65
	s_nop 0
	global_load_lds_dwordx4 v[158:159], off
	s_waitcnt vmcnt(8)
	s_waitcnt lgkmcnt(0)
	s_barrier
	s_waitcnt lgkmcnt(0)
	v_mfma_f32_16x16x32_bf16 v[158:161], v[84:87], v[104:107], v[170:173]
	v_mfma_f32_16x16x32_bf16 v[170:173], v[88:91], v[116:119], v[158:161]
	v_mfma_f32_16x16x32_bf16 v[72:75], v[92:95], v[104:107], v[72:75]
	v_mfma_f32_16x16x32_bf16 v[158:161], v[84:87], v[186:189], v[162:165]
	v_mfma_f32_16x16x32_bf16 v[60:63], v[92:95], v[186:189], v[60:63]
	v_mfma_f32_16x16x32_bf16 v[154:157], v[84:87], v[198:201], v[154:157]
	v_mfma_f32_16x16x32_bf16 v[48:51], v[92:95], v[198:201], v[48:51]
	v_mfma_f32_16x16x32_bf16 v[134:137], v[84:87], v[210:213], v[134:137]
	v_mfma_f32_16x16x32_bf16 v[36:39], v[92:95], v[210:213], v[36:39]
	v_mfma_f32_16x16x32_bf16 v[72:75], v[100:103], v[116:119], v[72:75]
	v_mfma_f32_16x16x32_bf16 v[162:165], v[88:91], v[190:193], v[158:161]
	v_mfma_f32_16x16x32_bf16 v[60:63], v[100:103], v[190:193], v[60:63]
	v_mfma_f32_16x16x32_bf16 v[154:157], v[88:91], v[206:209], v[154:157]
	v_mfma_f32_16x16x32_bf16 v[48:51], v[100:103], v[206:209], v[48:51]
	v_mfma_f32_16x16x32_bf16 v[134:137], v[88:91], v[214:217], v[134:137]
	v_mfma_f32_16x16x32_bf16 v[36:39], v[100:103], v[214:217], v[36:39]
	v_mfma_f32_16x16x32_bf16 v[158:161], v[112:115], v[104:107], v[166:169]
	v_mfma_f32_16x16x32_bf16 v[68:71], v[146:149], v[104:107], v[68:71]
	v_mfma_f32_16x16x32_bf16 v[104:107], v[112:115], v[186:189], v[138:141]
	v_mfma_f32_16x16x32_bf16 v[166:169], v[124:127], v[116:119], v[158:161]
	v_mfma_f32_16x16x32_bf16 v[158:161], v[124:127], v[190:193], v[104:107]
	v_mfma_f32_16x16x32_bf16 v[104:107], v[112:115], v[198:201], v[142:145]
	v_mfma_f32_16x16x32_bf16 v[56:59], v[146:149], v[186:189], v[56:59]
	v_mfma_f32_16x16x32_bf16 v[142:145], v[124:127], v[206:209], v[104:107]
	v_mfma_f32_16x16x32_bf16 v[44:47], v[146:149], v[198:201], v[44:47]
	v_mfma_f32_16x16x32_bf16 v[104:107], v[112:115], v[210:213], v[130:133]
	v_mfma_f32_16x16x32_bf16 v[32:35], v[146:149], v[210:213], v[32:35]
	v_mfma_f32_16x16x32_bf16 v[68:71], v[150:153], v[116:119], v[68:71]
	v_mfma_f32_16x16x32_bf16 v[56:59], v[150:153], v[190:193], v[56:59]
	v_mfma_f32_16x16x32_bf16 v[44:47], v[150:153], v[206:209], v[44:47]
	v_mfma_f32_16x16x32_bf16 v[130:133], v[124:127], v[214:217], v[104:107]
	v_mfma_f32_16x16x32_bf16 v[32:35], v[150:153], v[214:217], v[32:35]
	s_barrier
	s_add_i32 s28, s53, s61
	v_lshl_add_u64 v[116:117], v[218:219], 0, s[34:35]
	s_mov_b32 m0, s28
	ds_read_b128 v[104:107], v205 offset:49152
	ds_read_b128 v[138:141], v205 offset:50176
	ds_read_b128 v[186:189], v205 offset:51200
	ds_read_b128 v[190:193], v205 offset:52224
	ds_read_b128 v[198:201], v205 offset:53248
	ds_read_b128 v[206:209], v205 offset:54272
	ds_read_b128 v[210:213], v205 offset:55296
	ds_read_b128 v[214:217], v205 offset:56320
	global_load_lds_dwordx4 v[116:117], off
	v_lshl_add_u64 v[116:117], v[220:221], 0, s[34:35]
	s_add_i32 m0, s28, 0x2000
	s_add_i32 s28, s76, s61
	global_load_lds_dwordx4 v[116:117], off
	v_lshl_add_u64 v[116:117], v[222:223], 0, s[34:35]
	s_mov_b32 m0, s28
	s_nop 0
	global_load_lds_dwordx4 v[116:117], off
	v_lshl_add_u64 v[116:117], v[224:225], 0, s[34:35]
	s_add_i32 m0, s28, 0x2000
	s_nop 0
	global_load_lds_dwordx4 v[116:117], off
	v_lshl_add_u64 v[116:117], v[226:227], 0, s[34:35]
	s_mov_b32 m0, s67
	s_nop 0
	global_load_lds_dwordx4 v[116:117], off
	v_lshl_add_u64 v[116:117], v[228:229], 0, s[34:35]
	s_mov_b32 m0, s48
	s_nop 0
	global_load_lds_dwordx4 v[116:117], off
	s_waitcnt vmcnt(8)
	s_waitcnt lgkmcnt(0)
	s_barrier
	s_waitcnt lgkmcnt(0)
	v_mfma_f32_16x16x32_bf16 v[116:119], v[84:87], v[104:107], v[120:123]
	v_mfma_f32_16x16x32_bf16 v[28:31], v[92:95], v[104:107], v[28:31]
	v_mfma_f32_16x16x32_bf16 v[108:111], v[84:87], v[186:189], v[108:111]
	v_mfma_f32_16x16x32_bf16 v[20:23], v[92:95], v[186:189], v[20:23]
	v_mfma_f32_16x16x32_bf16 v[96:99], v[84:87], v[198:201], v[96:99]
	v_mfma_f32_16x16x32_bf16 v[12:15], v[92:95], v[198:201], v[12:15]
	v_mfma_f32_16x16x32_bf16 v[40:43], v[84:87], v[210:213], v[40:43]
	v_mfma_f32_16x16x32_bf16 v[4:7], v[92:95], v[210:213], v[4:7]
	v_mfma_f32_16x16x32_bf16 v[120:123], v[88:91], v[138:141], v[116:119]
	v_mfma_f32_16x16x32_bf16 v[28:31], v[100:103], v[138:141], v[28:31]
	v_mfma_f32_16x16x32_bf16 v[108:111], v[88:91], v[190:193], v[108:111]
	v_mfma_f32_16x16x32_bf16 v[20:23], v[100:103], v[190:193], v[20:23]
	v_mfma_f32_16x16x32_bf16 v[96:99], v[88:91], v[206:209], v[96:99]
	v_mfma_f32_16x16x32_bf16 v[12:15], v[100:103], v[206:209], v[12:15]
	v_mfma_f32_16x16x32_bf16 v[84:87], v[88:91], v[214:217], v[40:43]
	v_mfma_f32_16x16x32_bf16 v[4:7], v[100:103], v[214:217], v[4:7]
	v_mfma_f32_16x16x32_bf16 v[40:43], v[112:115], v[104:107], v[52:55]
	v_mfma_f32_16x16x32_bf16 v[116:119], v[124:127], v[138:141], v[40:43]
	v_mfma_f32_16x16x32_bf16 v[40:43], v[112:115], v[186:189], v[64:67]
	v_mfma_f32_16x16x32_bf16 v[24:27], v[146:149], v[104:107], v[24:27]
	v_mfma_f32_16x16x32_bf16 v[104:107], v[124:127], v[190:193], v[40:43]
	v_mfma_f32_16x16x32_bf16 v[40:43], v[112:115], v[198:201], v[76:79]
	v_mfma_f32_16x16x32_bf16 v[16:19], v[146:149], v[186:189], v[16:19]
	v_mfma_f32_16x16x32_bf16 v[92:95], v[124:127], v[206:209], v[40:43]
	v_mfma_f32_16x16x32_bf16 v[8:11], v[146:149], v[198:201], v[8:11]
	v_mfma_f32_16x16x32_bf16 v[40:43], v[112:115], v[210:213], v[80:83]
	v_mfma_f32_16x16x32_bf16 v[0:3], v[146:149], v[210:213], v[0:3]
	v_mfma_f32_16x16x32_bf16 v[24:27], v[150:153], v[138:141], v[24:27]
	v_mfma_f32_16x16x32_bf16 v[16:19], v[150:153], v[190:193], v[16:19]
	v_mfma_f32_16x16x32_bf16 v[8:11], v[150:153], v[206:209], v[8:11]
	v_mfma_f32_16x16x32_bf16 v[80:83], v[124:127], v[214:217], v[40:43]
	v_mfma_f32_16x16x32_bf16 v[0:3], v[150:153], v[214:217], v[0:3]
	s_barrier
	s_add_u32 s58, s58, 0x100
	s_addc_u32 s59, s59, 0
	s_add_u32 s18, s18, 0x100
	s_addc_u32 s33, s33, 0
	s_cmp_ge_i32 s52, s49
	s_mov_b32 s28, s52
	s_cbranch_scc0 .LBB0_1165
	s_mov_b32 s101, 1
	v_readlane_b32 s86, v255, 23
	v_readlane_b32 s87, v255, 24
	s_movk_i32 s76, 0x6000

.Lpro_4:
	s_mov_b32 s101, 0
	s_waitcnt vmcnt(8)
	s_barrier
	v_bfe_u32 v0, v146, 4, 2
	v_lshlrev_b32_e32 v2, 4, v0
	s_and_b32 s40, s36, 3
	s_ashr_i32 s53, s27, 6
	v_lshl_or_b32 v2, v147, 6, v2
	s_lshl_b32 s27, s37, 13
	v_and_b32_e32 v3, 32, v144
	v_bitop3_b32 v4, v2, s27, v3 bitop3:0xde
	s_lshl_b32 s27, s40, 12
	s_cmp_gt_i32 s26, 63
	v_bitop3_b32 v149, s27, v2, v3 bitop3:0xf6
	s_cselect_b64 s[26:27], -1, 0
	s_add_i32 s56, s53, -2
	v_lshlrev_b32_e32 v1, 3, v0
	s_cmpk_lt_u32 s33, 0x100
	v_cmp_eq_u32_e64 s[38:39], 0, v0
	v_add_u32_e32 v0, v14, v12
	v_lshl_or_b32 v148, s37, 6, v147
	s_waitcnt vmcnt(6)
	s_cselect_b64 s[36:37], -1, 0
	s_ashr_i32 s58, s4, 31
	s_ashr_i32 s59, s5, 31
	s_lshl_b32 s33, s40, 2
	v_add_lshl_u32 v128, v0, v13, 1
	v_add_u32_e32 v0, v17, v15
	s_add_u32 s60, s2, s33
	v_lshl_add_u64 v[138:139], s[14:15], 0, v[128:129]
	v_add_lshl_u32 v128, v0, v16, 1
	v_lshl_or_b32 v150, s40, 5, v1
	s_mov_b32 s57, 0
	s_addc_u32 s61, s3, 0
	v_lshl_add_u64 v[140:141], s[14:15], 0, v[128:129]
	v_add_u32_e32 v151, 0, v4
	s_barrier
	s_branch .LBB0_1634

.LBB0_1646:
	s_add_i32 s70, s28, 2
	s_add_u32 s71, s46, 0x80
	s_addc_u32 s29, s47, 0
	s_add_i32 s76, 0, 0x10000
	s_cmp_eq_u32 s56, s28
	s_cselect_b32 s29, s43, s29
	s_cselect_b32 s28, s42, s71
	v_add_u32_e32 v128, s76, v149
	s_cselect_b32 s73, s45, s67
	s_cselect_b32 s72, s44, s33
	s_add_i32 s71, 0, 0x14000
	ds_read_b128 v[152:155], v128
	ds_read_b128 v[156:159], v128 offset:1024
	ds_read_b128 v[160:163], v128 offset:2048
	ds_read_b128 v[164:167], v128 offset:3072
	v_add_u32_e32 v128, s71, v149
	ds_read_b128 v[168:171], v128
	ds_read_b128 v[172:175], v128 offset:1024
	ds_read_b128 v[176:179], v128 offset:2048
	ds_read_b128 v[180:183], v128 offset:3072
	v_lshl_add_u64 v[142:143], s[46:47], 0, v[138:139]
	s_add_i32 m0, s20, 0xc000
	ds_read_b128 v[184:187], v151
	ds_read_b128 v[188:191], v151 offset:1024
	ds_read_b128 v[192:195], v151 offset:2048
	ds_read_b128 v[196:199], v151 offset:3072
	ds_read_b128 v[200:203], v151 offset:4096
	ds_read_b128 v[204:207], v151 offset:5120
	ds_read_b128 v[208:211], v151 offset:6144
	ds_read_b128 v[212:215], v151 offset:7168
	global_load_lds_dwordx4 v[142:143], off
	v_lshl_add_u64 v[142:143], s[46:47], 0, v[140:141]
	s_add_i32 m0, s20, 0xe000
	s_nop 0
	global_load_lds_dwordx4 v[142:143], off
	s_cmp_eq_u32 s101, 0
	s_cbranch_scc1 .Lrx_strict_1646_0
	s_waitcnt vmcnt(40)
	s_branch .Lrx_join_1646_0

.Lrx_join_1646_0:
	s_waitcnt lgkmcnt(0)
	s_barrier
	s_waitcnt lgkmcnt(0)
	v_mfma_f32_16x16x32_bf16 v[120:123], v[152:155], v[184:187], v[120:123]
	v_mfma_f32_16x16x32_bf16 v[124:127], v[160:163], v[184:187], v[124:127]
	v_mfma_f32_16x16x32_bf16 v[108:111], v[152:155], v[192:195], v[108:111]
	v_mfma_f32_16x16x32_bf16 v[104:107], v[160:163], v[192:195], v[104:107]
	v_mfma_f32_16x16x32_bf16 v[92:95], v[152:155], v[200:203], v[92:95]
	v_mfma_f32_16x16x32_bf16 v[88:91], v[160:163], v[200:203], v[88:91]
	v_mfma_f32_16x16x32_bf16 v[76:79], v[152:155], v[208:211], v[76:79]
	v_mfma_f32_16x16x32_bf16 v[72:75], v[160:163], v[208:211], v[72:75]
	v_mfma_f32_16x16x32_bf16 v[120:123], v[156:159], v[188:191], v[120:123]
	v_mfma_f32_16x16x32_bf16 v[124:127], v[164:167], v[188:191], v[124:127]
	v_mfma_f32_16x16x32_bf16 v[108:111], v[156:159], v[196:199], v[108:111]
	v_mfma_f32_16x16x32_bf16 v[104:107], v[164:167], v[196:199], v[104:107]
	v_mfma_f32_16x16x32_bf16 v[92:95], v[156:159], v[204:207], v[92:95]
	v_mfma_f32_16x16x32_bf16 v[88:91], v[164:167], v[204:207], v[88:91]
	v_mfma_f32_16x16x32_bf16 v[76:79], v[156:159], v[212:215], v[76:79]
	v_mfma_f32_16x16x32_bf16 v[72:75], v[164:167], v[212:215], v[72:75]
	v_mfma_f32_16x16x32_bf16 v[116:119], v[168:171], v[184:187], v[116:119]
	v_mfma_f32_16x16x32_bf16 v[112:115], v[176:179], v[184:187], v[112:115]
	v_mfma_f32_16x16x32_bf16 v[100:103], v[168:171], v[192:195], v[100:103]
	v_mfma_f32_16x16x32_bf16 v[96:99], v[176:179], v[192:195], v[96:99]
	v_mfma_f32_16x16x32_bf16 v[84:87], v[168:171], v[200:203], v[84:87]
	v_mfma_f32_16x16x32_bf16 v[80:83], v[176:179], v[200:203], v[80:83]
	v_mfma_f32_16x16x32_bf16 v[68:71], v[168:171], v[208:211], v[68:71]
	v_mfma_f32_16x16x32_bf16 v[64:67], v[176:179], v[208:211], v[64:67]
	v_mfma_f32_16x16x32_bf16 v[116:119], v[172:175], v[188:191], v[116:119]
	v_mfma_f32_16x16x32_bf16 v[112:115], v[180:183], v[188:191], v[112:115]
	v_mfma_f32_16x16x32_bf16 v[100:103], v[172:175], v[196:199], v[100:103]
	v_mfma_f32_16x16x32_bf16 v[96:99], v[180:183], v[196:199], v[96:99]
	v_mfma_f32_16x16x32_bf16 v[84:87], v[172:175], v[204:207], v[84:87]
	v_mfma_f32_16x16x32_bf16 v[80:83], v[180:183], v[204:207], v[80:83]
	v_mfma_f32_16x16x32_bf16 v[68:71], v[172:175], v[212:215], v[68:71]
	v_mfma_f32_16x16x32_bf16 v[64:67], v[180:183], v[212:215], v[64:67]
	s_barrier
	s_add_i32 s76, s76, s18
	v_lshl_add_u64 v[142:143], s[72:73], 0, v[132:133]
	s_mov_b32 m0, s76
	ds_read_b128 v[184:187], v151 offset:16384
	ds_read_b128 v[188:191], v151 offset:17408
	ds_read_b128 v[192:195], v151 offset:18432
	ds_read_b128 v[196:199], v151 offset:19456
	ds_read_b128 v[200:203], v151 offset:20480
	ds_read_b128 v[204:207], v151 offset:21504
	ds_read_b128 v[208:211], v151 offset:22528
	ds_read_b128 v[212:215], v151 offset:23552
	global_load_lds_dwordx4 v[142:143], off
	s_add_i32 m0, s76, 0x2000
	v_lshl_add_u64 v[216:217], s[72:73], 0, v[136:137]
	s_add_u32 s72, s72, s14
	s_addc_u32 s73, s73, s15
	s_add_i32 s71, s71, s18
	global_load_lds_dwordx4 v[216:217], off
	v_lshl_add_u64 v[218:219], s[72:73], 0, v[132:133]
	s_mov_b32 m0, s71
	v_lshl_add_u64 v[220:221], s[72:73], 0, v[136:137]
	global_load_lds_dwordx4 v[218:219], off
	s_add_i32 m0, s71, 0x2000
	v_lshl_add_u64 v[222:223], s[28:29], 0, v[130:131]
	global_load_lds_dwordx4 v[220:221], off
	s_mov_b32 m0, s20
	v_lshl_add_u64 v[224:225], s[28:29], 0, v[134:135]
	global_load_lds_dwordx4 v[222:223], off
	s_mov_b32 m0, s48
	s_nop 0
	global_load_lds_dwordx4 v[224:225], off
	s_cmp_eq_u32 s101, 0
	s_cbranch_scc1 .Lrx_strict_1646_1
	s_waitcnt vmcnt(40)
	s_branch .Lrx_join_1646_1

.Lrx_join_1646_1:
	s_mov_b32 s101, 0
	s_waitcnt lgkmcnt(0)
	s_barrier
	s_waitcnt lgkmcnt(0)
	v_mfma_f32_16x16x32_bf16 v[60:63], v[152:155], v[184:187], v[60:63]
	v_mfma_f32_16x16x32_bf16 v[56:59], v[160:163], v[184:187], v[56:59]
	v_mfma_f32_16x16x32_bf16 v[44:47], v[152:155], v[192:195], v[44:47]
	v_mfma_f32_16x16x32_bf16 v[40:43], v[160:163], v[192:195], v[40:43]
	v_mfma_f32_16x16x32_bf16 v[28:31], v[152:155], v[200:203], v[28:31]
	v_mfma_f32_16x16x32_bf16 v[24:27], v[160:163], v[200:203], v[24:27]
	v_mfma_f32_16x16x32_bf16 v[12:15], v[152:155], v[208:211], v[12:15]
	v_mfma_f32_16x16x32_bf16 v[8:11], v[160:163], v[208:211], v[8:11]
	v_mfma_f32_16x16x32_bf16 v[60:63], v[156:159], v[188:191], v[60:63]
	v_mfma_f32_16x16x32_bf16 v[56:59], v[164:167], v[188:191], v[56:59]
	v_mfma_f32_16x16x32_bf16 v[44:47], v[156:159], v[196:199], v[44:47]
	v_mfma_f32_16x16x32_bf16 v[40:43], v[164:167], v[196:199], v[40:43]
	v_mfma_f32_16x16x32_bf16 v[28:31], v[156:159], v[204:207], v[28:31]
	v_mfma_f32_16x16x32_bf16 v[24:27], v[164:167], v[204:207], v[24:27]
	v_mfma_f32_16x16x32_bf16 v[12:15], v[156:159], v[212:215], v[12:15]
	v_mfma_f32_16x16x32_bf16 v[8:11], v[164:167], v[212:215], v[8:11]
	v_mfma_f32_16x16x32_bf16 v[52:55], v[168:171], v[184:187], v[52:55]
	v_mfma_f32_16x16x32_bf16 v[48:51], v[176:179], v[184:187], v[48:51]
	v_mfma_f32_16x16x32_bf16 v[36:39], v[168:171], v[192:195], v[36:39]
	v_mfma_f32_16x16x32_bf16 v[32:35], v[176:179], v[192:195], v[32:35]
	v_mfma_f32_16x16x32_bf16 v[20:23], v[168:171], v[200:203], v[20:23]
	v_mfma_f32_16x16x32_bf16 v[16:19], v[176:179], v[200:203], v[16:19]
	v_mfma_f32_16x16x32_bf16 v[4:7], v[168:171], v[208:211], v[4:7]
	v_mfma_f32_16x16x32_bf16 v[0:3], v[176:179], v[208:211], v[0:3]
	v_mfma_f32_16x16x32_bf16 v[52:55], v[172:175], v[188:191], v[52:55]
	v_mfma_f32_16x16x32_bf16 v[48:51], v[180:183], v[188:191], v[48:51]
	v_mfma_f32_16x16x32_bf16 v[36:39], v[172:175], v[196:199], v[36:39]
	v_mfma_f32_16x16x32_bf16 v[32:35], v[180:183], v[196:199], v[32:35]
	v_mfma_f32_16x16x32_bf16 v[20:23], v[172:175], v[204:207], v[20:23]
	v_mfma_f32_16x16x32_bf16 v[16:19], v[180:183], v[204:207], v[16:19]
	v_mfma_f32_16x16x32_bf16 v[4:7], v[172:175], v[212:215], v[4:7]
	v_mfma_f32_16x16x32_bf16 v[0:3], v[180:183], v[212:215], v[0:3]
	s_barrier
	s_add_i32 s71, 0, 0x18000
	v_add_u32_e32 v128, s71, v149
	s_add_i32 s72, 0, 0x1c000
	ds_read_b128 v[152:155], v128
	ds_read_b128 v[156:159], v128 offset:1024
	ds_read_b128 v[160:163], v128 offset:2048
	ds_read_b128 v[164:167], v128 offset:3072
	v_add_u32_e32 v128, s72, v149
	ds_read_b128 v[168:171], v128
	ds_read_b128 v[172:175], v128 offset:1024
	ds_read_b128 v[176:179], v128 offset:2048
	ds_read_b128 v[180:183], v128 offset:3072
	s_add_u32 s28, s28, s14
	s_addc_u32 s29, s29, s15
	s_mov_b32 m0, s49
	v_lshl_add_u64 v[226:227], s[28:29], 0, v[130:131]
	ds_read_b128 v[184:187], v151 offset:32768
	ds_read_b128 v[188:191], v151 offset:33792
	ds_read_b128 v[192:195], v151 offset:34816
	ds_read_b128 v[196:199], v151 offset:35840
	ds_read_b128 v[200:203], v151 offset:36864
	ds_read_b128 v[204:207], v151 offset:37888
	ds_read_b128 v[208:211], v151 offset:38912
	ds_read_b128 v[212:215], v151 offset:39936
	global_load_lds_dwordx4 v[226:227], off
	v_lshl_add_u64 v[226:227], s[28:29], 0, v[134:135]
	s_mov_b32 m0, s50
	s_nop 0
	global_load_lds_dwordx4 v[226:227], off
	s_waitcnt vmcnt(8)
	s_waitcnt lgkmcnt(0)
	s_barrier
	s_waitcnt lgkmcnt(0)
	v_mfma_f32_16x16x32_bf16 v[120:123], v[152:155], v[184:187], v[120:123]
	v_mfma_f32_16x16x32_bf16 v[124:127], v[160:163], v[184:187], v[124:127]
	v_mfma_f32_16x16x32_bf16 v[108:111], v[152:155], v[192:195], v[108:111]
	v_mfma_f32_16x16x32_bf16 v[104:107], v[160:163], v[192:195], v[104:107]
	v_mfma_f32_16x16x32_bf16 v[92:95], v[152:155], v[200:203], v[92:95]
	v_mfma_f32_16x16x32_bf16 v[88:91], v[160:163], v[200:203], v[88:91]
	v_mfma_f32_16x16x32_bf16 v[76:79], v[152:155], v[208:211], v[76:79]
	v_mfma_f32_16x16x32_bf16 v[72:75], v[160:163], v[208:211], v[72:75]
	v_mfma_f32_16x16x32_bf16 v[120:123], v[156:159], v[188:191], v[120:123]
	v_mfma_f32_16x16x32_bf16 v[124:127], v[164:167], v[188:191], v[124:127]
	v_mfma_f32_16x16x32_bf16 v[108:111], v[156:159], v[196:199], v[108:111]
	v_mfma_f32_16x16x32_bf16 v[104:107], v[164:167], v[196:199], v[104:107]
	v_mfma_f32_16x16x32_bf16 v[92:95], v[156:159], v[204:207], v[92:95]
	v_mfma_f32_16x16x32_bf16 v[88:91], v[164:167], v[204:207], v[88:91]
	v_mfma_f32_16x16x32_bf16 v[76:79], v[156:159], v[212:215], v[76:79]
	v_mfma_f32_16x16x32_bf16 v[72:75], v[164:167], v[212:215], v[72:75]
	v_mfma_f32_16x16x32_bf16 v[116:119], v[168:171], v[184:187], v[116:119]
	v_mfma_f32_16x16x32_bf16 v[112:115], v[176:179], v[184:187], v[112:115]
	v_mfma_f32_16x16x32_bf16 v[100:103], v[168:171], v[192:195], v[100:103]
	v_mfma_f32_16x16x32_bf16 v[96:99], v[176:179], v[192:195], v[96:99]
	v_mfma_f32_16x16x32_bf16 v[84:87], v[168:171], v[200:203], v[84:87]
	v_mfma_f32_16x16x32_bf16 v[80:83], v[176:179], v[200:203], v[80:83]
	v_mfma_f32_16x16x32_bf16 v[68:71], v[168:171], v[208:211], v[68:71]
	v_mfma_f32_16x16x32_bf16 v[64:67], v[176:179], v[208:211], v[64:67]
	v_mfma_f32_16x16x32_bf16 v[116:119], v[172:175], v[188:191], v[116:119]
	v_mfma_f32_16x16x32_bf16 v[112:115], v[180:183], v[188:191], v[112:115]
	v_mfma_f32_16x16x32_bf16 v[100:103], v[172:175], v[196:199], v[100:103]
	v_mfma_f32_16x16x32_bf16 v[96:99], v[180:183], v[196:199], v[96:99]
	v_mfma_f32_16x16x32_bf16 v[84:87], v[172:175], v[204:207], v[84:87]
	v_mfma_f32_16x16x32_bf16 v[80:83], v[180:183], v[204:207], v[80:83]
	v_mfma_f32_16x16x32_bf16 v[68:71], v[172:175], v[212:215], v[68:71]
	v_mfma_f32_16x16x32_bf16 v[64:67], v[180:183], v[212:215], v[64:67]
	s_barrier
	s_add_i32 s28, s71, s18
	v_lshl_add_u64 v[142:143], v[142:143], 0, s[34:35]
	s_mov_b32 m0, s28
	ds_read_b128 v[184:187], v151 offset:49152
	ds_read_b128 v[188:191], v151 offset:50176
	ds_read_b128 v[192:195], v151 offset:51200
	ds_read_b128 v[196:199], v151 offset:52224
	ds_read_b128 v[200:203], v151 offset:53248
	ds_read_b128 v[204:207], v151 offset:54272
	ds_read_b128 v[208:211], v151 offset:55296
	ds_read_b128 v[212:215], v151 offset:56320
	global_load_lds_dwordx4 v[142:143], off
	v_lshl_add_u64 v[142:143], v[216:217], 0, s[34:35]
	s_add_i32 m0, s28, 0x2000
	s_add_i32 s28, s72, s18
	global_load_lds_dwordx4 v[142:143], off
	v_lshl_add_u64 v[142:143], v[218:219], 0, s[34:35]
	s_mov_b32 m0, s28
	s_nop 0
	global_load_lds_dwordx4 v[142:143], off
	v_lshl_add_u64 v[142:143], v[220:221], 0, s[34:35]
	s_add_i32 m0, s28, 0x2000
	s_nop 0
	global_load_lds_dwordx4 v[142:143], off
	v_lshl_add_u64 v[142:143], v[222:223], 0, s[34:35]
	s_mov_b32 m0, s51
	s_nop 0
	global_load_lds_dwordx4 v[142:143], off
	v_lshl_add_u64 v[142:143], v[224:225], 0, s[34:35]
	s_mov_b32 m0, s52
	s_nop 0
	global_load_lds_dwordx4 v[142:143], off
	s_waitcnt vmcnt(8)
	s_waitcnt lgkmcnt(0)
	s_barrier
	s_waitcnt lgkmcnt(0)
	v_mfma_f32_16x16x32_bf16 v[60:63], v[152:155], v[184:187], v[60:63]
	v_mfma_f32_16x16x32_bf16 v[56:59], v[160:163], v[184:187], v[56:59]
	v_mfma_f32_16x16x32_bf16 v[44:47], v[152:155], v[192:195], v[44:47]
	v_mfma_f32_16x16x32_bf16 v[40:43], v[160:163], v[192:195], v[40:43]
	v_mfma_f32_16x16x32_bf16 v[28:31], v[152:155], v[200:203], v[28:31]
	v_mfma_f32_16x16x32_bf16 v[24:27], v[160:163], v[200:203], v[24:27]
	v_mfma_f32_16x16x32_bf16 v[12:15], v[152:155], v[208:211], v[12:15]
	v_mfma_f32_16x16x32_bf16 v[8:11], v[160:163], v[208:211], v[8:11]
	v_mfma_f32_16x16x32_bf16 v[60:63], v[156:159], v[188:191], v[60:63]
	v_mfma_f32_16x16x32_bf16 v[56:59], v[164:167], v[188:191], v[56:59]
	v_mfma_f32_16x16x32_bf16 v[44:47], v[156:159], v[196:199], v[44:47]
	v_mfma_f32_16x16x32_bf16 v[40:43], v[164:167], v[196:199], v[40:43]
	v_mfma_f32_16x16x32_bf16 v[28:31], v[156:159], v[204:207], v[28:31]
	v_mfma_f32_16x16x32_bf16 v[24:27], v[164:167], v[204:207], v[24:27]
	v_mfma_f32_16x16x32_bf16 v[12:15], v[156:159], v[212:215], v[12:15]
	v_mfma_f32_16x16x32_bf16 v[8:11], v[164:167], v[212:215], v[8:11]
	v_mfma_f32_16x16x32_bf16 v[52:55], v[168:171], v[184:187], v[52:55]
	v_mfma_f32_16x16x32_bf16 v[48:51], v[176:179], v[184:187], v[48:51]
	v_mfma_f32_16x16x32_bf16 v[36:39], v[168:171], v[192:195], v[36:39]
	v_mfma_f32_16x16x32_bf16 v[32:35], v[176:179], v[192:195], v[32:35]
	v_mfma_f32_16x16x32_bf16 v[20:23], v[168:171], v[200:203], v[20:23]
	v_mfma_f32_16x16x32_bf16 v[16:19], v[176:179], v[200:203], v[16:19]
	v_mfma_f32_16x16x32_bf16 v[4:7], v[168:171], v[208:211], v[4:7]
	v_mfma_f32_16x16x32_bf16 v[0:3], v[176:179], v[208:211], v[0:3]
	v_mfma_f32_16x16x32_bf16 v[52:55], v[172:175], v[188:191], v[52:55]
	v_mfma_f32_16x16x32_bf16 v[48:51], v[180:183], v[188:191], v[48:51]
	v_mfma_f32_16x16x32_bf16 v[36:39], v[172:175], v[196:199], v[36:39]
	v_mfma_f32_16x16x32_bf16 v[32:35], v[180:183], v[196:199], v[32:35]
	v_mfma_f32_16x16x32_bf16 v[20:23], v[172:175], v[204:207], v[20:23]
	v_mfma_f32_16x16x32_bf16 v[16:19], v[180:183], v[204:207], v[16:19]
	v_mfma_f32_16x16x32_bf16 v[4:7], v[172:175], v[212:215], v[4:7]
	v_mfma_f32_16x16x32_bf16 v[0:3], v[180:183], v[212:215], v[0:3]
	s_barrier
	s_add_u32 s46, s46, 0x100
	s_addc_u32 s47, s47, 0
	s_add_u32 s33, s33, 0x100
	s_addc_u32 s67, s67, 0
	s_cmp_ge_i32 s70, s53
	s_mov_b32 s28, s70
	s_cbranch_scc0 .LBB0_1646
	s_mov_b32 s101, 1
	s_movk_i32 s76, 0x6000

.LBB0_1756:
	s_add_i32 s43, s28, 2
	s_add_u32 s46, s40, 0x80
	s_addc_u32 s29, s41, 0
	s_add_i32 s64, 0, 0x10000
	s_cmp_eq_u32 s97, s28
	s_cselect_b32 s29, s61, s29
	s_cselect_b32 s28, s60, s46
	v_add_u32_e32 v128, s64, v195
	s_cselect_b32 s47, s63, s42
	s_cselect_b32 s46, s62, s33
	s_add_i32 s65, 0, 0x14000
	ds_read_b128 v[130:133], v128
	ds_read_b128 v[134:137], v128 offset:1024
	ds_read_b128 v[138:141], v128 offset:2048
	ds_read_b128 v[142:145], v128 offset:3072
	v_add_u32_e32 v128, s65, v195
	ds_read_b128 v[164:167], v128
	s_waitcnt lgkmcnt(0)
	ds_read_b128 v[168:171], v128 offset:1024
	ds_read_b128 v[172:175], v128 offset:2048
	ds_read_b128 v[176:179], v128 offset:3072
	v_lshl_add_u64 v[192:193], s[40:41], 0, v[160:161]
	s_add_i32 m0, s7, 0xc000
	ds_read_b128 v[180:183], v202
	ds_read_b128 v[184:187], v202 offset:1024
	ds_read_b128 v[188:191], v202 offset:2048
	ds_read_b128 v[204:207], v202 offset:3072
	ds_read_b128 v[208:211], v202 offset:4096
	ds_read_b128 v[212:215], v202 offset:5120
	ds_read_b128 v[216:219], v202 offset:6144
	ds_read_b128 v[220:223], v202 offset:7168
	global_load_lds_dwordx4 v[192:193], off
	v_lshl_add_u64 v[192:193], s[40:41], 0, v[162:163]
	s_add_i32 m0, s7, 0xe000
	s_nop 0
	global_load_lds_dwordx4 v[192:193], off
	s_waitcnt vmcnt(8)
	s_waitcnt lgkmcnt(0)
	s_barrier
	s_waitcnt lgkmcnt(0)
	v_mfma_f32_16x16x32_bf16 v[112:115], v[130:133], v[180:183], v[112:115]
	v_mfma_f32_16x16x32_bf16 v[124:127], v[138:141], v[180:183], v[124:127]
	v_mfma_f32_16x16x32_bf16 v[100:103], v[130:133], v[188:191], v[100:103]
	v_mfma_f32_16x16x32_bf16 v[108:111], v[138:141], v[188:191], v[108:111]
	v_mfma_f32_16x16x32_bf16 v[84:87], v[130:133], v[208:211], v[84:87]
	v_mfma_f32_16x16x32_bf16 v[92:95], v[138:141], v[208:211], v[92:95]
	v_mfma_f32_16x16x32_bf16 v[68:71], v[130:133], v[216:219], v[68:71]
	v_mfma_f32_16x16x32_bf16 v[76:79], v[138:141], v[216:219], v[76:79]
	v_mfma_f32_16x16x32_bf16 v[112:115], v[134:137], v[184:187], v[112:115]
	v_mfma_f32_16x16x32_bf16 v[124:127], v[142:145], v[184:187], v[124:127]
	v_mfma_f32_16x16x32_bf16 v[100:103], v[134:137], v[204:207], v[100:103]
	v_mfma_f32_16x16x32_bf16 v[108:111], v[142:145], v[204:207], v[108:111]
	v_mfma_f32_16x16x32_bf16 v[84:87], v[134:137], v[212:215], v[84:87]
	v_mfma_f32_16x16x32_bf16 v[92:95], v[142:145], v[212:215], v[92:95]
	v_mfma_f32_16x16x32_bf16 v[68:71], v[134:137], v[220:223], v[68:71]
	v_mfma_f32_16x16x32_bf16 v[76:79], v[142:145], v[220:223], v[76:79]
	v_mfma_f32_16x16x32_bf16 v[116:119], v[164:167], v[180:183], v[116:119]
	v_mfma_f32_16x16x32_bf16 v[120:123], v[172:175], v[180:183], v[120:123]
	v_mfma_f32_16x16x32_bf16 v[96:99], v[164:167], v[188:191], v[96:99]
	v_mfma_f32_16x16x32_bf16 v[104:107], v[172:175], v[188:191], v[104:107]
	v_mfma_f32_16x16x32_bf16 v[80:83], v[164:167], v[208:211], v[80:83]
	v_mfma_f32_16x16x32_bf16 v[88:91], v[172:175], v[208:211], v[88:91]
	v_mfma_f32_16x16x32_bf16 v[64:67], v[164:167], v[216:219], v[64:67]
	v_mfma_f32_16x16x32_bf16 v[72:75], v[172:175], v[216:219], v[72:75]
	v_mfma_f32_16x16x32_bf16 v[116:119], v[168:171], v[184:187], v[116:119]
	v_mfma_f32_16x16x32_bf16 v[120:123], v[176:179], v[184:187], v[120:123]
	v_mfma_f32_16x16x32_bf16 v[96:99], v[168:171], v[204:207], v[96:99]
	v_mfma_f32_16x16x32_bf16 v[104:107], v[176:179], v[204:207], v[104:107]
	v_mfma_f32_16x16x32_bf16 v[80:83], v[168:171], v[212:215], v[80:83]
	v_mfma_f32_16x16x32_bf16 v[88:91], v[176:179], v[212:215], v[88:91]
	v_mfma_f32_16x16x32_bf16 v[64:67], v[168:171], v[220:223], v[64:67]
	v_mfma_f32_16x16x32_bf16 v[72:75], v[176:179], v[220:223], v[72:75]
	s_barrier
	s_add_i32 s64, s64, s4
	v_lshl_add_u64 v[192:193], s[46:47], 0, v[150:151]
	s_mov_b32 m0, s64
	ds_read_b128 v[180:183], v202 offset:16384
	ds_read_b128 v[184:187], v202 offset:17408
	ds_read_b128 v[188:191], v202 offset:18432
	ds_read_b128 v[204:207], v202 offset:19456
	ds_read_b128 v[208:211], v202 offset:20480
	ds_read_b128 v[212:215], v202 offset:21504
	ds_read_b128 v[216:219], v202 offset:22528
	ds_read_b128 v[220:223], v202 offset:23552
	global_load_lds_dwordx4 v[192:193], off
	s_add_i32 m0, s64, 0x2000
	v_lshl_add_u64 v[198:199], s[46:47], 0, v[154:155]
	s_add_u32 s46, s46, s14
	s_addc_u32 s47, s47, s15
	s_add_i32 s64, s65, s4
	global_load_lds_dwordx4 v[198:199], off
	v_lshl_add_u64 v[200:201], s[46:47], 0, v[150:151]
	s_mov_b32 m0, s64
	v_lshl_add_u64 v[224:225], s[46:47], 0, v[154:155]
	global_load_lds_dwordx4 v[200:201], off
	s_add_i32 m0, s64, 0x2000
	v_lshl_add_u64 v[226:227], s[28:29], 0, v[148:149]
	global_load_lds_dwordx4 v[224:225], off
	s_mov_b32 m0, s7
	v_lshl_add_u64 v[228:229], s[28:29], 0, v[152:153]
	global_load_lds_dwordx4 v[226:227], off
	s_mov_b32 m0, s48
	s_nop 0
	global_load_lds_dwordx4 v[228:229], off
	s_waitcnt vmcnt(8)
	s_waitcnt lgkmcnt(0)
	s_barrier
	s_waitcnt lgkmcnt(0)
	v_mfma_f32_16x16x32_bf16 v[52:55], v[130:133], v[180:183], v[52:55]
	v_mfma_f32_16x16x32_bf16 v[60:63], v[138:141], v[180:183], v[60:63]
	v_mfma_f32_16x16x32_bf16 v[36:39], v[130:133], v[188:191], v[36:39]
	v_mfma_f32_16x16x32_bf16 v[44:47], v[138:141], v[188:191], v[44:47]
	v_mfma_f32_16x16x32_bf16 v[20:23], v[130:133], v[208:211], v[20:23]
	v_mfma_f32_16x16x32_bf16 v[28:31], v[138:141], v[208:211], v[28:31]
	v_mfma_f32_16x16x32_bf16 v[12:15], v[130:133], v[216:219], v[12:15]
	v_mfma_f32_16x16x32_bf16 v[4:7], v[138:141], v[216:219], v[4:7]
	v_mfma_f32_16x16x32_bf16 v[52:55], v[134:137], v[184:187], v[52:55]
	v_mfma_f32_16x16x32_bf16 v[60:63], v[142:145], v[184:187], v[60:63]
	v_mfma_f32_16x16x32_bf16 v[36:39], v[134:137], v[204:207], v[36:39]
	v_mfma_f32_16x16x32_bf16 v[44:47], v[142:145], v[204:207], v[44:47]
	v_mfma_f32_16x16x32_bf16 v[20:23], v[134:137], v[212:215], v[20:23]
	v_mfma_f32_16x16x32_bf16 v[28:31], v[142:145], v[212:215], v[28:31]
	v_mfma_f32_16x16x32_bf16 v[12:15], v[134:137], v[220:223], v[12:15]
	v_mfma_f32_16x16x32_bf16 v[4:7], v[142:145], v[220:223], v[4:7]
	v_mfma_f32_16x16x32_bf16 v[48:51], v[164:167], v[180:183], v[48:51]
	v_mfma_f32_16x16x32_bf16 v[56:59], v[172:175], v[180:183], v[56:59]
	v_mfma_f32_16x16x32_bf16 v[32:35], v[164:167], v[188:191], v[32:35]
	v_mfma_f32_16x16x32_bf16 v[40:43], v[172:175], v[188:191], v[40:43]
	v_mfma_f32_16x16x32_bf16 v[16:19], v[164:167], v[208:211], v[16:19]
	v_mfma_f32_16x16x32_bf16 v[24:27], v[172:175], v[208:211], v[24:27]
	v_mfma_f32_16x16x32_bf16 v[8:11], v[164:167], v[216:219], v[8:11]
	v_mfma_f32_16x16x32_bf16 v[0:3], v[172:175], v[216:219], v[0:3]
	v_mfma_f32_16x16x32_bf16 v[48:51], v[168:171], v[184:187], v[48:51]
	v_mfma_f32_16x16x32_bf16 v[56:59], v[176:179], v[184:187], v[56:59]
	v_mfma_f32_16x16x32_bf16 v[32:35], v[168:171], v[204:207], v[32:35]
	v_mfma_f32_16x16x32_bf16 v[40:43], v[176:179], v[204:207], v[40:43]
	v_mfma_f32_16x16x32_bf16 v[16:19], v[168:171], v[212:215], v[16:19]
	v_mfma_f32_16x16x32_bf16 v[24:27], v[176:179], v[212:215], v[24:27]
	v_mfma_f32_16x16x32_bf16 v[8:11], v[168:171], v[220:223], v[8:11]
	v_mfma_f32_16x16x32_bf16 v[0:3], v[176:179], v[220:223], v[0:3]
	s_barrier
	s_add_i32 s46, 0, 0x18000
	v_add_u32_e32 v128, s46, v195
	s_add_i32 s47, 0, 0x1c000
	ds_read_b128 v[130:133], v128
	ds_read_b128 v[134:137], v128 offset:1024
	ds_read_b128 v[138:141], v128 offset:2048
	ds_read_b128 v[142:145], v128 offset:3072
	v_add_u32_e32 v128, s47, v195
	ds_read_b128 v[164:167], v128
	ds_read_b128 v[168:171], v128 offset:1024
	ds_read_b128 v[172:175], v128 offset:2048
	ds_read_b128 v[176:179], v128 offset:3072
	s_add_u32 s28, s28, s14
	s_addc_u32 s29, s29, s15
	s_mov_b32 m0, s49
	v_lshl_add_u64 v[230:231], s[28:29], 0, v[148:149]
	ds_read_b128 v[180:183], v202 offset:32768
	ds_read_b128 v[184:187], v202 offset:33792
	ds_read_b128 v[188:191], v202 offset:34816
	ds_read_b128 v[204:207], v202 offset:35840
	ds_read_b128 v[208:211], v202 offset:36864
	ds_read_b128 v[212:215], v202 offset:37888
	ds_read_b128 v[216:219], v202 offset:38912
	ds_read_b128 v[220:223], v202 offset:39936
	global_load_lds_dwordx4 v[230:231], off
	v_lshl_add_u64 v[230:231], s[28:29], 0, v[152:153]
	s_mov_b32 m0, s89
	s_nop 0
	global_load_lds_dwordx4 v[230:231], off
	s_waitcnt vmcnt(8)
	s_waitcnt lgkmcnt(0)
	s_barrier
	s_waitcnt lgkmcnt(0)
	v_mfma_f32_16x16x32_bf16 v[112:115], v[130:133], v[180:183], v[112:115]
	v_mfma_f32_16x16x32_bf16 v[124:127], v[138:141], v[180:183], v[124:127]
	v_mfma_f32_16x16x32_bf16 v[100:103], v[130:133], v[188:191], v[100:103]
	v_mfma_f32_16x16x32_bf16 v[108:111], v[138:141], v[188:191], v[108:111]
	v_mfma_f32_16x16x32_bf16 v[84:87], v[130:133], v[208:211], v[84:87]
	v_mfma_f32_16x16x32_bf16 v[92:95], v[138:141], v[208:211], v[92:95]
	v_mfma_f32_16x16x32_bf16 v[68:71], v[130:133], v[216:219], v[68:71]
	v_mfma_f32_16x16x32_bf16 v[76:79], v[138:141], v[216:219], v[76:79]
	v_mfma_f32_16x16x32_bf16 v[112:115], v[134:137], v[184:187], v[112:115]
	v_mfma_f32_16x16x32_bf16 v[124:127], v[142:145], v[184:187], v[124:127]
	v_mfma_f32_16x16x32_bf16 v[100:103], v[134:137], v[204:207], v[100:103]
	v_mfma_f32_16x16x32_bf16 v[108:111], v[142:145], v[204:207], v[108:111]
	v_mfma_f32_16x16x32_bf16 v[84:87], v[134:137], v[212:215], v[84:87]
	v_mfma_f32_16x16x32_bf16 v[92:95], v[142:145], v[212:215], v[92:95]
	v_mfma_f32_16x16x32_bf16 v[68:71], v[134:137], v[220:223], v[68:71]
	v_mfma_f32_16x16x32_bf16 v[76:79], v[142:145], v[220:223], v[76:79]
	v_mfma_f32_16x16x32_bf16 v[116:119], v[164:167], v[180:183], v[116:119]
	v_mfma_f32_16x16x32_bf16 v[120:123], v[172:175], v[180:183], v[120:123]
	v_mfma_f32_16x16x32_bf16 v[96:99], v[164:167], v[188:191], v[96:99]
	v_mfma_f32_16x16x32_bf16 v[104:107], v[172:175], v[188:191], v[104:107]
	v_mfma_f32_16x16x32_bf16 v[80:83], v[164:167], v[208:211], v[80:83]
	v_mfma_f32_16x16x32_bf16 v[88:91], v[172:175], v[208:211], v[88:91]
	v_mfma_f32_16x16x32_bf16 v[64:67], v[164:167], v[216:219], v[64:67]
	v_mfma_f32_16x16x32_bf16 v[72:75], v[172:175], v[216:219], v[72:75]
	v_mfma_f32_16x16x32_bf16 v[116:119], v[168:171], v[184:187], v[116:119]
	v_mfma_f32_16x16x32_bf16 v[120:123], v[176:179], v[184:187], v[120:123]
	v_mfma_f32_16x16x32_bf16 v[96:99], v[168:171], v[204:207], v[96:99]
	v_mfma_f32_16x16x32_bf16 v[104:107], v[176:179], v[204:207], v[104:107]
	v_mfma_f32_16x16x32_bf16 v[80:83], v[168:171], v[212:215], v[80:83]
	v_mfma_f32_16x16x32_bf16 v[88:91], v[176:179], v[212:215], v[88:91]
	v_mfma_f32_16x16x32_bf16 v[64:67], v[168:171], v[220:223], v[64:67]
	v_mfma_f32_16x16x32_bf16 v[72:75], v[176:179], v[220:223], v[72:75]
	s_barrier
	s_add_i32 s28, s46, s4
	v_lshl_add_u64 v[192:193], v[192:193], 0, s[34:35]
	s_mov_b32 m0, s28
	ds_read_b128 v[180:183], v202 offset:49152
	ds_read_b128 v[184:187], v202 offset:50176
	ds_read_b128 v[188:191], v202 offset:51200
	ds_read_b128 v[204:207], v202 offset:52224
	ds_read_b128 v[208:211], v202 offset:53248
	ds_read_b128 v[212:215], v202 offset:54272
	ds_read_b128 v[216:219], v202 offset:55296
	ds_read_b128 v[220:223], v202 offset:56320
	global_load_lds_dwordx4 v[192:193], off
	v_lshl_add_u64 v[192:193], v[198:199], 0, s[34:35]
	s_add_i32 m0, s28, 0x2000
	s_add_i32 s28, s47, s4
	global_load_lds_dwordx4 v[192:193], off
	v_lshl_add_u64 v[192:193], v[200:201], 0, s[34:35]
	s_mov_b32 m0, s28
	s_nop 0
	global_load_lds_dwordx4 v[192:193], off
	v_lshl_add_u64 v[192:193], v[224:225], 0, s[34:35]
	s_add_i32 m0, s28, 0x2000
	s_nop 0
	global_load_lds_dwordx4 v[192:193], off
	v_lshl_add_u64 v[192:193], v[226:227], 0, s[34:35]
	s_mov_b32 m0, s95
	s_nop 0
	global_load_lds_dwordx4 v[192:193], off
	v_lshl_add_u64 v[192:193], v[228:229], 0, s[34:35]
	s_mov_b32 m0, s96
	s_nop 0
	global_load_lds_dwordx4 v[192:193], off
	s_waitcnt vmcnt(8)
	s_waitcnt lgkmcnt(0)
	s_barrier
	s_waitcnt lgkmcnt(0)
	v_mfma_f32_16x16x32_bf16 v[52:55], v[130:133], v[180:183], v[52:55]
	v_mfma_f32_16x16x32_bf16 v[60:63], v[138:141], v[180:183], v[60:63]
	v_mfma_f32_16x16x32_bf16 v[36:39], v[130:133], v[188:191], v[36:39]
	v_mfma_f32_16x16x32_bf16 v[44:47], v[138:141], v[188:191], v[44:47]
	v_mfma_f32_16x16x32_bf16 v[20:23], v[130:133], v[208:211], v[20:23]
	v_mfma_f32_16x16x32_bf16 v[28:31], v[138:141], v[208:211], v[28:31]
	v_mfma_f32_16x16x32_bf16 v[12:15], v[130:133], v[216:219], v[12:15]
	v_mfma_f32_16x16x32_bf16 v[4:7], v[138:141], v[216:219], v[4:7]
	v_mfma_f32_16x16x32_bf16 v[52:55], v[134:137], v[184:187], v[52:55]
	v_mfma_f32_16x16x32_bf16 v[60:63], v[142:145], v[184:187], v[60:63]
	v_mfma_f32_16x16x32_bf16 v[36:39], v[134:137], v[204:207], v[36:39]
	v_mfma_f32_16x16x32_bf16 v[44:47], v[142:145], v[204:207], v[44:47]
	v_mfma_f32_16x16x32_bf16 v[20:23], v[134:137], v[212:215], v[20:23]
	v_mfma_f32_16x16x32_bf16 v[28:31], v[142:145], v[212:215], v[28:31]
	v_mfma_f32_16x16x32_bf16 v[12:15], v[134:137], v[220:223], v[12:15]
	v_mfma_f32_16x16x32_bf16 v[4:7], v[142:145], v[220:223], v[4:7]
	v_mfma_f32_16x16x32_bf16 v[48:51], v[164:167], v[180:183], v[48:51]
	v_mfma_f32_16x16x32_bf16 v[56:59], v[172:175], v[180:183], v[56:59]
	v_mfma_f32_16x16x32_bf16 v[32:35], v[164:167], v[188:191], v[32:35]
	v_mfma_f32_16x16x32_bf16 v[40:43], v[172:175], v[188:191], v[40:43]
	v_mfma_f32_16x16x32_bf16 v[16:19], v[164:167], v[208:211], v[16:19]
	v_mfma_f32_16x16x32_bf16 v[24:27], v[172:175], v[208:211], v[24:27]
	v_mfma_f32_16x16x32_bf16 v[8:11], v[164:167], v[216:219], v[8:11]
	v_mfma_f32_16x16x32_bf16 v[0:3], v[172:175], v[216:219], v[0:3]
	v_mfma_f32_16x16x32_bf16 v[48:51], v[168:171], v[184:187], v[48:51]
	v_mfma_f32_16x16x32_bf16 v[56:59], v[176:179], v[184:187], v[56:59]
	v_mfma_f32_16x16x32_bf16 v[32:35], v[168:171], v[204:207], v[32:35]
	v_mfma_f32_16x16x32_bf16 v[40:43], v[176:179], v[204:207], v[40:43]
	v_mfma_f32_16x16x32_bf16 v[16:19], v[168:171], v[212:215], v[16:19]
	v_mfma_f32_16x16x32_bf16 v[24:27], v[176:179], v[212:215], v[24:27]
	v_mfma_f32_16x16x32_bf16 v[8:11], v[168:171], v[220:223], v[8:11]
	v_mfma_f32_16x16x32_bf16 v[0:3], v[176:179], v[220:223], v[0:3]
	s_barrier
	s_add_u32 s40, s40, 0x100
	s_addc_u32 s41, s41, 0
	s_add_u32 s33, s33, 0x100
	s_addc_u32 s42, s42, 0
	s_cmp_ge_i32 s43, s91
	s_mov_b32 s28, s43
	s_cbranch_scc0 .LBB0_1756

.Lpro_7:
	s_mov_b32 s101, 0
	s_waitcnt vmcnt(8)
	s_barrier
	v_lshrrev_b32_e32 v0, 1, v150
	v_and_b32_e32 v0, 24, v0
	v_lshlrev_b32_e32 v1, 1, v0
	v_lshl_or_b32 v1, v151, 6, v1
	s_lshl_b32 s37, s38, 13
	v_and_b32_e32 v2, 32, v130
	v_bitop3_b32 v3, v1, s37, v2 bitop3:0xde
	s_lshl_b32 s37, s39, 5
	s_add_i32 s20, s36, s20
	s_and_b32 s39, s37, 0x60
	s_ashr_i32 s20, s20, 6
	s_lshl_b32 s37, s39, 7
	s_cmp_gt_i32 s36, 63
	v_bitop3_b32 v153, s37, v1, v2 bitop3:0xf6
	s_cselect_b64 s[36:37], -1, 0
	s_add_i32 s56, s20, -2
	s_cmpk_lt_u32 s33, 0x100
	v_or_b32_e32 v159, s39, v0
	v_add_u32_e32 v0, v14, v12
	s_cselect_b64 s[42:43], -1, 0
	s_lshl_b32 s33, s38, 8
	v_add_lshl_u32 v0, v0, v13, 1
	v_mov_b32_e32 v1, v129
	s_waitcnt vmcnt(6)
	s_add_i32 s33, s33, 0
	v_lshl_add_u64 v[138:139], s[22:23], 0, v[0:1]
	v_add_u32_e32 v0, v17, v15
	v_lshl_or_b32 v152, s38, 6, v151
	s_add_i32 s33, s33, 0x20800
	v_add_lshl_u32 v0, v0, v16, 1
	v_add_u32_e32 v154, 0x80, v152
	v_add_u32_e32 v155, 0x90, v152
	v_add_u32_e32 v156, 0xa0, v152
	v_add_u32_e32 v157, 0xb0, v152
	v_add_u32_e32 v158, s33, v130
	v_lshl_add_u64 v[140:141], s[22:23], 0, v[0:1]
	s_mov_b32 s62, 0
	v_add_u32_e32 v160, 0, v3
	s_barrier
	s_branch .LBB0_2307

.LBB0_2319:
	s_add_i32 s64, s28, 2
	s_add_u32 s65, s46, 0x80
	s_addc_u32 s29, s47, 0
	s_add_i32 s67, 0, 0x10000
	s_cmp_eq_u32 s56, s28
	s_cselect_b32 s29, s41, s29
	s_cselect_b32 s28, s40, s65
	v_add_u32_e32 v161, s67, v153
	s_cselect_b32 s71, s45, s63
	s_cselect_b32 s70, s44, s33
	s_add_i32 s65, 0, 0x14000
	ds_read_b128 v[142:145], v161
	ds_read_b128 v[146:149], v161 offset:1024
	ds_read_b128 v[162:165], v161 offset:2048
	ds_read_b128 v[166:169], v161 offset:3072
	v_add_u32_e32 v161, s65, v153
	ds_read_b128 v[170:173], v161
	ds_read_b128 v[174:177], v161 offset:1024
	ds_read_b128 v[178:181], v161 offset:2048
	ds_read_b128 v[182:185], v161 offset:3072
	v_lshl_add_u64 v[218:219], s[46:47], 0, v[138:139]
	s_add_i32 m0, s48, 0xc000
	ds_read_b128 v[186:189], v160
	ds_read_b128 v[190:193], v160 offset:1024
	ds_read_b128 v[194:197], v160 offset:2048
	ds_read_b128 v[198:201], v160 offset:3072
	ds_read_b128 v[202:205], v160 offset:4096
	ds_read_b128 v[206:209], v160 offset:5120
	ds_read_b128 v[210:213], v160 offset:6144
	ds_read_b128 v[214:217], v160 offset:7168
	global_load_lds_dwordx4 v[218:219], off
	v_lshl_add_u64 v[218:219], s[46:47], 0, v[140:141]
	s_add_i32 m0, s48, 0xe000
	s_nop 0
	global_load_lds_dwordx4 v[218:219], off
	s_cmp_eq_u32 s101, 0
	s_cbranch_scc1 .Lrx_strict_2319_0
	s_waitcnt vmcnt(24)
	s_branch .Lrx_join_2319_0

.Lrx_join_2319_0:
	s_waitcnt lgkmcnt(0)
	s_barrier
	s_waitcnt lgkmcnt(0)
	v_mfma_f32_16x16x32_bf16 v[124:127], v[142:145], v[186:189], v[124:127]
	v_mfma_f32_16x16x32_bf16 v[120:123], v[162:165], v[186:189], v[120:123]
	v_mfma_f32_16x16x32_bf16 v[108:111], v[142:145], v[194:197], v[108:111]
	v_mfma_f32_16x16x32_bf16 v[104:107], v[162:165], v[194:197], v[104:107]
	v_mfma_f32_16x16x32_bf16 v[92:95], v[142:145], v[202:205], v[92:95]
	v_mfma_f32_16x16x32_bf16 v[88:91], v[162:165], v[202:205], v[88:91]
	v_mfma_f32_16x16x32_bf16 v[76:79], v[142:145], v[210:213], v[76:79]
	v_mfma_f32_16x16x32_bf16 v[72:75], v[162:165], v[210:213], v[72:75]
	v_mfma_f32_16x16x32_bf16 v[124:127], v[146:149], v[190:193], v[124:127]
	v_mfma_f32_16x16x32_bf16 v[120:123], v[166:169], v[190:193], v[120:123]
	v_mfma_f32_16x16x32_bf16 v[108:111], v[146:149], v[198:201], v[108:111]
	v_mfma_f32_16x16x32_bf16 v[104:107], v[166:169], v[198:201], v[104:107]
	v_mfma_f32_16x16x32_bf16 v[92:95], v[146:149], v[206:209], v[92:95]
	v_mfma_f32_16x16x32_bf16 v[88:91], v[166:169], v[206:209], v[88:91]
	v_mfma_f32_16x16x32_bf16 v[76:79], v[146:149], v[214:217], v[76:79]
	v_mfma_f32_16x16x32_bf16 v[72:75], v[166:169], v[214:217], v[72:75]
	v_mfma_f32_16x16x32_bf16 v[116:119], v[170:173], v[186:189], v[116:119]
	v_mfma_f32_16x16x32_bf16 v[112:115], v[178:181], v[186:189], v[112:115]
	v_mfma_f32_16x16x32_bf16 v[100:103], v[170:173], v[194:197], v[100:103]
	v_mfma_f32_16x16x32_bf16 v[96:99], v[178:181], v[194:197], v[96:99]
	v_mfma_f32_16x16x32_bf16 v[84:87], v[170:173], v[202:205], v[84:87]
	v_mfma_f32_16x16x32_bf16 v[80:83], v[178:181], v[202:205], v[80:83]
	v_mfma_f32_16x16x32_bf16 v[68:71], v[170:173], v[210:213], v[68:71]
	v_mfma_f32_16x16x32_bf16 v[64:67], v[178:181], v[210:213], v[64:67]
	v_mfma_f32_16x16x32_bf16 v[116:119], v[174:177], v[190:193], v[116:119]
	v_mfma_f32_16x16x32_bf16 v[112:115], v[182:185], v[190:193], v[112:115]
	v_mfma_f32_16x16x32_bf16 v[100:103], v[174:177], v[198:201], v[100:103]
	v_mfma_f32_16x16x32_bf16 v[96:99], v[182:185], v[198:201], v[96:99]
	v_mfma_f32_16x16x32_bf16 v[84:87], v[174:177], v[206:209], v[84:87]
	v_mfma_f32_16x16x32_bf16 v[80:83], v[182:185], v[206:209], v[80:83]
	v_mfma_f32_16x16x32_bf16 v[68:71], v[174:177], v[214:217], v[68:71]
	v_mfma_f32_16x16x32_bf16 v[64:67], v[182:185], v[214:217], v[64:67]
	s_barrier
	s_add_i32 s67, s67, s6
	v_lshl_add_u64 v[218:219], s[70:71], 0, v[128:129]
	s_mov_b32 m0, s67
	ds_read_b128 v[186:189], v160 offset:16384
	ds_read_b128 v[190:193], v160 offset:17408
	ds_read_b128 v[194:197], v160 offset:18432
	ds_read_b128 v[198:201], v160 offset:19456
	ds_read_b128 v[202:205], v160 offset:20480
	ds_read_b128 v[206:209], v160 offset:21504
	ds_read_b128 v[210:213], v160 offset:22528
	ds_read_b128 v[214:217], v160 offset:23552
	global_load_lds_dwordx4 v[218:219], off
	s_add_i32 m0, s67, 0x2000
	v_lshl_add_u64 v[220:221], s[70:71], 0, v[136:137]
	s_add_u32 s70, s70, s22
	s_addc_u32 s71, s71, s23
	s_add_i32 s65, s65, s6
	global_load_lds_dwordx4 v[220:221], off
	v_lshl_add_u64 v[222:223], s[70:71], 0, v[128:129]
	s_mov_b32 m0, s65
	v_lshl_add_u64 v[224:225], s[70:71], 0, v[136:137]
	global_load_lds_dwordx4 v[222:223], off
	s_add_i32 m0, s65, 0x2000
	v_lshl_add_u64 v[226:227], s[28:29], 0, v[132:133]
	global_load_lds_dwordx4 v[224:225], off
	s_mov_b32 m0, s48
	v_lshl_add_u64 v[228:229], s[28:29], 0, v[134:135]
	global_load_lds_dwordx4 v[226:227], off
	s_mov_b32 m0, s49
	s_nop 0
	global_load_lds_dwordx4 v[228:229], off
	s_cmp_eq_u32 s101, 0
	s_cbranch_scc1 .Lrx_strict_2319_1
	s_waitcnt vmcnt(24)
	s_branch .Lrx_join_2319_1

.Lrx_join_2319_1:
	s_mov_b32 s101, 0
	s_waitcnt lgkmcnt(0)
	s_barrier
	s_waitcnt lgkmcnt(0)
	v_mfma_f32_16x16x32_bf16 v[60:63], v[142:145], v[186:189], v[60:63]
	v_mfma_f32_16x16x32_bf16 v[56:59], v[162:165], v[186:189], v[56:59]
	v_mfma_f32_16x16x32_bf16 v[44:47], v[142:145], v[194:197], v[44:47]
	v_mfma_f32_16x16x32_bf16 v[40:43], v[162:165], v[194:197], v[40:43]
	v_mfma_f32_16x16x32_bf16 v[28:31], v[142:145], v[202:205], v[28:31]
	v_mfma_f32_16x16x32_bf16 v[24:27], v[162:165], v[202:205], v[24:27]
	v_mfma_f32_16x16x32_bf16 v[12:15], v[142:145], v[210:213], v[12:15]
	v_mfma_f32_16x16x32_bf16 v[8:11], v[162:165], v[210:213], v[8:11]
	v_mfma_f32_16x16x32_bf16 v[60:63], v[146:149], v[190:193], v[60:63]
	v_mfma_f32_16x16x32_bf16 v[56:59], v[166:169], v[190:193], v[56:59]
	v_mfma_f32_16x16x32_bf16 v[44:47], v[146:149], v[198:201], v[44:47]
	v_mfma_f32_16x16x32_bf16 v[40:43], v[166:169], v[198:201], v[40:43]
	v_mfma_f32_16x16x32_bf16 v[28:31], v[146:149], v[206:209], v[28:31]
	v_mfma_f32_16x16x32_bf16 v[24:27], v[166:169], v[206:209], v[24:27]
	v_mfma_f32_16x16x32_bf16 v[12:15], v[146:149], v[214:217], v[12:15]
	v_mfma_f32_16x16x32_bf16 v[8:11], v[166:169], v[214:217], v[8:11]
	v_mfma_f32_16x16x32_bf16 v[52:55], v[170:173], v[186:189], v[52:55]
	v_mfma_f32_16x16x32_bf16 v[48:51], v[178:181], v[186:189], v[48:51]
	v_mfma_f32_16x16x32_bf16 v[36:39], v[170:173], v[194:197], v[36:39]
	v_mfma_f32_16x16x32_bf16 v[32:35], v[178:181], v[194:197], v[32:35]
	v_mfma_f32_16x16x32_bf16 v[20:23], v[170:173], v[202:205], v[20:23]
	v_mfma_f32_16x16x32_bf16 v[16:19], v[178:181], v[202:205], v[16:19]
	v_mfma_f32_16x16x32_bf16 v[4:7], v[170:173], v[210:213], v[4:7]
	v_mfma_f32_16x16x32_bf16 v[0:3], v[178:181], v[210:213], v[0:3]
	v_mfma_f32_16x16x32_bf16 v[52:55], v[174:177], v[190:193], v[52:55]
	v_mfma_f32_16x16x32_bf16 v[48:51], v[182:185], v[190:193], v[48:51]
	v_mfma_f32_16x16x32_bf16 v[36:39], v[174:177], v[198:201], v[36:39]
	v_mfma_f32_16x16x32_bf16 v[32:35], v[182:185], v[198:201], v[32:35]
	v_mfma_f32_16x16x32_bf16 v[20:23], v[174:177], v[206:209], v[20:23]
	v_mfma_f32_16x16x32_bf16 v[16:19], v[182:185], v[206:209], v[16:19]
	v_mfma_f32_16x16x32_bf16 v[4:7], v[174:177], v[214:217], v[4:7]
	v_mfma_f32_16x16x32_bf16 v[0:3], v[182:185], v[214:217], v[0:3]
	s_barrier
	s_add_i32 s65, 0, 0x18000
	v_add_u32_e32 v161, s65, v153
	s_add_i32 s67, 0, 0x1c000
	ds_read_b128 v[142:145], v161
	ds_read_b128 v[146:149], v161 offset:1024
	ds_read_b128 v[162:165], v161 offset:2048
	ds_read_b128 v[166:169], v161 offset:3072
	v_add_u32_e32 v161, s67, v153
	ds_read_b128 v[170:173], v161
	ds_read_b128 v[174:177], v161 offset:1024
	ds_read_b128 v[178:181], v161 offset:2048
	ds_read_b128 v[182:185], v161 offset:3072
	s_add_u32 s28, s28, s22
	s_addc_u32 s29, s29, s23
	s_mov_b32 m0, s50
	v_lshl_add_u64 v[230:231], s[28:29], 0, v[132:133]
	ds_read_b128 v[186:189], v160 offset:32768
	ds_read_b128 v[190:193], v160 offset:33792
	ds_read_b128 v[194:197], v160 offset:34816
	ds_read_b128 v[198:201], v160 offset:35840
	ds_read_b128 v[202:205], v160 offset:36864
	ds_read_b128 v[206:209], v160 offset:37888
	ds_read_b128 v[210:213], v160 offset:38912
	ds_read_b128 v[214:217], v160 offset:39936
	global_load_lds_dwordx4 v[230:231], off
	v_lshl_add_u64 v[230:231], s[28:29], 0, v[134:135]
	s_mov_b32 m0, s51
	s_nop 0
	global_load_lds_dwordx4 v[230:231], off
	s_waitcnt vmcnt(8)
	s_waitcnt lgkmcnt(0)
	s_barrier
	s_waitcnt lgkmcnt(0)
	v_mfma_f32_16x16x32_bf16 v[124:127], v[142:145], v[186:189], v[124:127]
	v_mfma_f32_16x16x32_bf16 v[120:123], v[162:165], v[186:189], v[120:123]
	v_mfma_f32_16x16x32_bf16 v[108:111], v[142:145], v[194:197], v[108:111]
	v_mfma_f32_16x16x32_bf16 v[104:107], v[162:165], v[194:197], v[104:107]
	v_mfma_f32_16x16x32_bf16 v[92:95], v[142:145], v[202:205], v[92:95]
	v_mfma_f32_16x16x32_bf16 v[88:91], v[162:165], v[202:205], v[88:91]
	v_mfma_f32_16x16x32_bf16 v[76:79], v[142:145], v[210:213], v[76:79]
	v_mfma_f32_16x16x32_bf16 v[72:75], v[162:165], v[210:213], v[72:75]
	v_mfma_f32_16x16x32_bf16 v[124:127], v[146:149], v[190:193], v[124:127]
	v_mfma_f32_16x16x32_bf16 v[120:123], v[166:169], v[190:193], v[120:123]
	v_mfma_f32_16x16x32_bf16 v[108:111], v[146:149], v[198:201], v[108:111]
	v_mfma_f32_16x16x32_bf16 v[104:107], v[166:169], v[198:201], v[104:107]
	v_mfma_f32_16x16x32_bf16 v[92:95], v[146:149], v[206:209], v[92:95]
	v_mfma_f32_16x16x32_bf16 v[88:91], v[166:169], v[206:209], v[88:91]
	v_mfma_f32_16x16x32_bf16 v[76:79], v[146:149], v[214:217], v[76:79]
	v_mfma_f32_16x16x32_bf16 v[72:75], v[166:169], v[214:217], v[72:75]
	v_mfma_f32_16x16x32_bf16 v[116:119], v[170:173], v[186:189], v[116:119]
	v_mfma_f32_16x16x32_bf16 v[112:115], v[178:181], v[186:189], v[112:115]
	v_mfma_f32_16x16x32_bf16 v[100:103], v[170:173], v[194:197], v[100:103]
	v_mfma_f32_16x16x32_bf16 v[96:99], v[178:181], v[194:197], v[96:99]
	v_mfma_f32_16x16x32_bf16 v[84:87], v[170:173], v[202:205], v[84:87]
	v_mfma_f32_16x16x32_bf16 v[80:83], v[178:181], v[202:205], v[80:83]
	v_mfma_f32_16x16x32_bf16 v[68:71], v[170:173], v[210:213], v[68:71]
	v_mfma_f32_16x16x32_bf16 v[64:67], v[178:181], v[210:213], v[64:67]
	v_mfma_f32_16x16x32_bf16 v[116:119], v[174:177], v[190:193], v[116:119]
	v_mfma_f32_16x16x32_bf16 v[112:115], v[182:185], v[190:193], v[112:115]
	v_mfma_f32_16x16x32_bf16 v[100:103], v[174:177], v[198:201], v[100:103]
	v_mfma_f32_16x16x32_bf16 v[96:99], v[182:185], v[198:201], v[96:99]
	v_mfma_f32_16x16x32_bf16 v[84:87], v[174:177], v[206:209], v[84:87]
	v_mfma_f32_16x16x32_bf16 v[80:83], v[182:185], v[206:209], v[80:83]
	v_mfma_f32_16x16x32_bf16 v[68:71], v[174:177], v[214:217], v[68:71]
	v_mfma_f32_16x16x32_bf16 v[64:67], v[182:185], v[214:217], v[64:67]
	s_barrier
	s_add_i32 s28, s65, s6
	v_lshl_add_u64 v[218:219], v[218:219], 0, s[34:35]
	s_mov_b32 m0, s28
	ds_read_b128 v[186:189], v160 offset:49152
	ds_read_b128 v[190:193], v160 offset:50176
	ds_read_b128 v[194:197], v160 offset:51200
	ds_read_b128 v[198:201], v160 offset:52224
	ds_read_b128 v[202:205], v160 offset:53248
	ds_read_b128 v[206:209], v160 offset:54272
	ds_read_b128 v[210:213], v160 offset:55296
	ds_read_b128 v[214:217], v160 offset:56320
	global_load_lds_dwordx4 v[218:219], off
	v_lshl_add_u64 v[218:219], v[220:221], 0, s[34:35]
	s_add_i32 m0, s28, 0x2000
	s_add_i32 s28, s67, s6
	global_load_lds_dwordx4 v[218:219], off
	v_lshl_add_u64 v[218:219], v[222:223], 0, s[34:35]
	s_mov_b32 m0, s28
	s_nop 0
	global_load_lds_dwordx4 v[218:219], off
	v_lshl_add_u64 v[218:219], v[224:225], 0, s[34:35]
	s_add_i32 m0, s28, 0x2000
	s_nop 0
	global_load_lds_dwordx4 v[218:219], off
	v_lshl_add_u64 v[218:219], v[226:227], 0, s[34:35]
	s_mov_b32 m0, s52
	s_nop 0
	global_load_lds_dwordx4 v[218:219], off
	v_lshl_add_u64 v[218:219], v[228:229], 0, s[34:35]
	s_mov_b32 m0, s53
	s_nop 0
	global_load_lds_dwordx4 v[218:219], off
	s_waitcnt vmcnt(8)
	s_waitcnt lgkmcnt(0)
	s_barrier
	s_waitcnt lgkmcnt(0)
	v_mfma_f32_16x16x32_bf16 v[60:63], v[142:145], v[186:189], v[60:63]
	v_mfma_f32_16x16x32_bf16 v[56:59], v[162:165], v[186:189], v[56:59]
	v_mfma_f32_16x16x32_bf16 v[44:47], v[142:145], v[194:197], v[44:47]
	v_mfma_f32_16x16x32_bf16 v[40:43], v[162:165], v[194:197], v[40:43]
	v_mfma_f32_16x16x32_bf16 v[28:31], v[142:145], v[202:205], v[28:31]
	v_mfma_f32_16x16x32_bf16 v[24:27], v[162:165], v[202:205], v[24:27]
	v_mfma_f32_16x16x32_bf16 v[12:15], v[142:145], v[210:213], v[12:15]
	v_mfma_f32_16x16x32_bf16 v[8:11], v[162:165], v[210:213], v[8:11]
	v_mfma_f32_16x16x32_bf16 v[60:63], v[146:149], v[190:193], v[60:63]
	v_mfma_f32_16x16x32_bf16 v[56:59], v[166:169], v[190:193], v[56:59]
	v_mfma_f32_16x16x32_bf16 v[44:47], v[146:149], v[198:201], v[44:47]
	v_mfma_f32_16x16x32_bf16 v[40:43], v[166:169], v[198:201], v[40:43]
	v_mfma_f32_16x16x32_bf16 v[28:31], v[146:149], v[206:209], v[28:31]
	v_mfma_f32_16x16x32_bf16 v[24:27], v[166:169], v[206:209], v[24:27]
	v_mfma_f32_16x16x32_bf16 v[12:15], v[146:149], v[214:217], v[12:15]
	v_mfma_f32_16x16x32_bf16 v[8:11], v[166:169], v[214:217], v[8:11]
	v_mfma_f32_16x16x32_bf16 v[52:55], v[170:173], v[186:189], v[52:55]
	v_mfma_f32_16x16x32_bf16 v[48:51], v[178:181], v[186:189], v[48:51]
	v_mfma_f32_16x16x32_bf16 v[36:39], v[170:173], v[194:197], v[36:39]
	v_mfma_f32_16x16x32_bf16 v[32:35], v[178:181], v[194:197], v[32:35]
	v_mfma_f32_16x16x32_bf16 v[20:23], v[170:173], v[202:205], v[20:23]
	v_mfma_f32_16x16x32_bf16 v[16:19], v[178:181], v[202:205], v[16:19]
	v_mfma_f32_16x16x32_bf16 v[4:7], v[170:173], v[210:213], v[4:7]
	v_mfma_f32_16x16x32_bf16 v[0:3], v[178:181], v[210:213], v[0:3]
	v_mfma_f32_16x16x32_bf16 v[52:55], v[174:177], v[190:193], v[52:55]
	v_mfma_f32_16x16x32_bf16 v[48:51], v[182:185], v[190:193], v[48:51]
	v_mfma_f32_16x16x32_bf16 v[36:39], v[174:177], v[198:201], v[36:39]
	v_mfma_f32_16x16x32_bf16 v[32:35], v[182:185], v[198:201], v[32:35]
	v_mfma_f32_16x16x32_bf16 v[20:23], v[174:177], v[206:209], v[20:23]
	v_mfma_f32_16x16x32_bf16 v[16:19], v[182:185], v[206:209], v[16:19]
	v_mfma_f32_16x16x32_bf16 v[4:7], v[174:177], v[214:217], v[4:7]
	v_mfma_f32_16x16x32_bf16 v[0:3], v[182:185], v[214:217], v[0:3]
	s_barrier
	s_add_u32 s46, s46, 0x100
	s_addc_u32 s47, s47, 0
	s_add_u32 s33, s33, 0x100
	s_addc_u32 s63, s63, 0
	s_cmp_ge_i32 s64, s20
	s_mov_b32 s28, s64
	s_cbranch_scc0 .LBB0_2319
.LBB0_2320:
	s_mov_b32 s101, 1
	s_and_b64 vcc, exec, s[42:43]
	s_cbranch_vccz .LBB0_2322
	s_barrier

	.amdhsa_kernel _Z10fwd_kernel4Args
		.amdhsa_group_segment_fixed_size 0
		.amdhsa_private_segment_fixed_size 0
		.amdhsa_kernarg_size 696
		.amdhsa_user_sgpr_count 2
		.amdhsa_user_sgpr_dispatch_ptr 0
		.amdhsa_user_sgpr_queue_ptr 0
		.amdhsa_user_sgpr_kernarg_segment_ptr 1
		.amdhsa_user_sgpr_dispatch_id 0
		.amdhsa_user_sgpr_kernarg_preload_length 0
		.amdhsa_user_sgpr_kernarg_preload_offset 0
		.amdhsa_user_sgpr_private_segment_size 0
		.amdhsa_uses_dynamic_stack 0
		.amdhsa_enable_private_segment 0
		.amdhsa_system_sgpr_workgroup_id_x 1
		.amdhsa_system_sgpr_workgroup_id_y 0
		.amdhsa_system_sgpr_workgroup_id_z 0
		.amdhsa_system_sgpr_workgroup_info 0
		.amdhsa_system_vgpr_workitem_id 0
		.amdhsa_next_free_vgpr 256
		.amdhsa_next_free_sgpr 102
		.amdhsa_accum_offset 256
		.amdhsa_reserve_vcc 1
		.amdhsa_float_round_mode_32 0
		.amdhsa_float_round_mode_16_64 0
		.amdhsa_float_denorm_mode_32 3
		.amdhsa_float_denorm_mode_16_64 3
		.amdhsa_dx10_clamp 1
		.amdhsa_ieee_mode 1
		.amdhsa_fp16_overflow 0
		.amdhsa_tg_split 0
		.amdhsa_exception_fp_ieee_invalid_op 0
		.amdhsa_exception_fp_denorm_src 0
		.amdhsa_exception_fp_ieee_div_zero 0
		.amdhsa_exception_fp_ieee_overflow 0
		.amdhsa_exception_fp_ieee_underflow 0
		.amdhsa_exception_fp_ieee_inexact 0
		.amdhsa_exception_int_div_zero 0
	.end_amdhsa_kernel

amdhsa.kernels:
  - .agpr_count:     0
    .args:
      - .offset:         0
        .size:           440
        .value_kind:     by_value
      - .offset:         440
        .size:           4
        .value_kind:     hidden_block_count_x
      - .offset:         444
        .size:           4
        .value_kind:     hidden_block_count_y
      - .offset:         448
        .size:           4
        .value_kind:     hidden_block_count_z
      - .offset:         452
        .size:           2
        .value_kind:     hidden_group_size_x
      - .offset:         454
        .size:           2
        .value_kind:     hidden_group_size_y
      - .offset:         456
        .size:           2
        .value_kind:     hidden_group_size_z
      - .offset:         458
        .size:           2
        .value_kind:     hidden_remainder_x
      - .offset:         460
        .size:           2
        .value_kind:     hidden_remainder_y
      - .offset:         462
        .size:           2
        .value_kind:     hidden_remainder_z
      - .offset:         480
        .size:           8
        .value_kind:     hidden_global_offset_x
      - .offset:         488
        .size:           8
        .value_kind:     hidden_global_offset_y
      - .offset:         496
        .size:           8
        .value_kind:     hidden_global_offset_z
      - .offset:         504
        .size:           2
        .value_kind:     hidden_grid_dims
      - .offset:         560
        .size:           4
        .value_kind:     hidden_dynamic_lds_size
    .group_segment_fixed_size: 0
    .kernarg_segment_align: 8
    .kernarg_segment_size: 696
    .language:       OpenCL C
    .language_version:
      - 2
      - 0
    .max_flat_workgroup_size: 512
    .name:           _Z10fwd_kernel4Args
    .private_segment_fixed_size: 0
    .sgpr_count:     108
    .sgpr_spill_count: 183
    .symbol:         _Z10fwd_kernel4Args.kd
    .uniform_work_group_size: 1
    .uses_dynamic_stack: false
    .vgpr_count:     256
    .vgpr_spill_count: 0
    .wavefront_size: 64
